# hand-scheduled RWKV recurrence (parity reduce-scatter layout, packed ops with broadcast operand in src0) + queue + compact rank
# speedup vs baseline: 1.0336x; 1.0184x over previous
; #define LAS __attribute__((address_space(3)))
; DI unsigned pk2(float a, float b) { f32x2 v = {a, b}; bf2_t r = __builtin_convertvector(v, bf2_t); return __builtin_bit_cast(unsigned, r); }
; DI f32x2 red16p(f32x2 x) { float a = x.x, b = x.y; red16x2(a, b); return (f32x2){a, b}; }
; DI void scan_bh2(const Args& a, int l, int bh, int halfsel, LAS unsigned char* lds) {
;     ...
;             const LAS float* cur = opbuf + (c & 1) * CH;
;             LAS unsigned char* yb = ybuf + (c & 1) * (T * 128);
;             f32x4 r4 = *(const LAS f32x4*)(cur + kq * 4), d4 = *(const LAS f32x4*)(cur + 64 + kq * 4), k4 = *(const LAS f32x4*)(cur + 128 + kq * 4),
;                   kk4 = *(const LAS f32x4*)(cur + 192 + kq * 4), b4 = *(const LAS f32x4*)(cur + 256 + kq * 4);
;             f32x2 v2 = *(const LAS f32x2*)(cur + 320 + row0);
; #pragma unroll
;             for (int st = 0; st < T; ++st) {
;                 f32x4 nr4, nd4, nk4, nkk4, nb4; f32x2 nv2;
;                 if (st < T - 1) {
;                     const LAS float* o = cur + (st + 1) * 384;
;                     nr4 = *(const LAS f32x4*)(o + kq * 4); nd4 = *(const LAS f32x4*)(o + 64 + kq * 4); nk4 = *(const LAS f32x4*)(o + 128 + kq * 4);
;                     nkk4 = *(const LAS f32x4*)(o + 192 + kq * 4); nb4 = *(const LAS f32x4*)(o + 256 + kq * 4); nv2 = *(const LAS f32x2*)(o + 320 + row0);
;                 }
;                 f32x2 sa = S[0] * kk4[0]; sa += S[1] * kk4[1]; f32x2 sb = S[2] * kk4[2]; sb += S[3] * kk4[3]; sa += sb;
;                 sa = red16p(sa); sa = -sa;
; #pragma unroll
;                 for (int j = 0; j < 4; ++j) S[j] = S[j] * d4[j] + sa * b4[j] + v2 * k4[j];
;                 f32x2 y = S[0] * r4[0]; y += S[1] * r4[1]; f32x2 yc = S[2] * r4[2]; yc += S[3] * r4[3]; y += yc;
;                 y = red16p(y);
;                 *(LAS unsigned*)(yb + st * 128 + row0 * 2) = pk2(y.x, y.y);
;                 if (st < T - 1) { r4 = nr4; d4 = nd4; k4 = nk4; kk4 = nkk4; b4 = nb4; v2 = nv2; }
.LBB0_497:
	s_and_b32 s2, s4, 1
	s_mul_i32 s3, s2, 0xc000
	s_lshl_b32 s2, s2, 12
	s_add_i32 s5, s2, 0x18000
	v_lshrrev_b32_e32 v254, 2, v11
	v_xor_b32_e32 v254, v254, v11
	v_bfe_u32 v254, v254, 2, 1
	v_add_u32_e32 v255, v10, v254
	v_xor_b32_e32 v254, 1, v254
	v_add_u32_e32 v254, v10, v254
	v_lshl_add_u32 v250, v11, 2, s3
	v_lshl_add_u32 v251, v255, 2, s3
	v_lshl_add_u32 v252, v254, 2, s3
	v_sub_u32_e32 v254, v255, v10
	v_lshl_add_u32 v253, v10, 1, s5
	v_mov_b32_e32 v255, 0x21000
	v_cmp_eq_u32_e64 s[2:3], 0, v254
	s_nop 1
	v_cndmask_b32_e64 v253, v255, v253, s[2:3]
	ds_read_b128 v[28:31], v250 offset:768
	ds_read_b32 v36, v251 offset:1280
	ds_read_b32 v37, v252 offset:1280
	ds_read_b128 v[24:27], v250 offset:512
	ds_read_b128 v[20:23], v250 offset:256
	ds_read_b128 v[32:35], v250 offset:1024
	ds_read_b128 v[16:19], v250 offset:0
	ds_read_b128 v[50:53], v250 offset:2304
	ds_read_b32 v58, v251 offset:2816
	ds_read_b32 v59, v252 offset:2816
	ds_read_b128 v[46:49], v250 offset:2048
	ds_read_b128 v[42:45], v250 offset:1792
	s_waitcnt lgkmcnt(5)
	v_pk_mul_f32 v[60:61], v[28:29], v[2:3] op_sel:[0,0] op_sel_hi:[0,1]
	v_pk_mul_f32 v[64:65], v[24:25], v[36:37] op_sel:[0,0] op_sel_hi:[0,1]
	v_pk_fma_f32 v[60:61], v[28:29], v[4:5], v[60:61] op_sel:[1,0,0] op_sel_hi:[1,1,1]
	v_pk_mul_f32 v[14:15], v[24:25], v[36:37] op_sel:[1,0] op_sel_hi:[1,1]
	v_pk_fma_f32 v[60:61], v[30:31], v[6:7], v[60:61] op_sel:[0,0,0] op_sel_hi:[0,1,1]
	v_pk_fma_f32 v[2:3], v[20:21], v[2:3], v[64:65] op_sel:[0,0,0] op_sel_hi:[0,1,1]
	v_pk_fma_f32 v[60:61], v[30:31], v[8:9], v[60:61] op_sel:[1,0,0] op_sel_hi:[1,1,1]
	v_pk_fma_f32 v[4:5], v[20:21], v[4:5], v[14:15] op_sel:[1,0,0] op_sel_hi:[1,1,1]
	v_pk_mul_f32 v[64:65], v[26:27], v[36:37] op_sel:[0,0] op_sel_hi:[0,1]
	v_add_f32_dpp v60, v61, v60 quad_perm:[1,0,3,2] row_mask:0xf bank_mask:0xf bound_ctrl:1
	v_pk_mul_f32 v[14:15], v[26:27], v[36:37] op_sel:[1,0] op_sel_hi:[1,1]
	v_pk_fma_f32 v[6:7], v[22:23], v[6:7], v[64:65] op_sel:[0,0,0] op_sel_hi:[0,1,1]
	v_add_f32_dpp v60, v60, v60 quad_perm:[2,3,0,1] row_mask:0xf bank_mask:0xf bound_ctrl:1
	v_pk_fma_f32 v[8:9], v[22:23], v[8:9], v[14:15] op_sel:[1,0,0] op_sel_hi:[1,1,1]
	s_nop 0
	v_add_f32_dpp v60, v60, v60 row_half_mirror row_mask:0xf bank_mask:0xf bound_ctrl:1
	ds_read_b128 v[54:57], v250 offset:2560
	s_nop 0
	v_add_f32_dpp v60, v60, v60 row_mirror row_mask:0xf bank_mask:0xf bound_ctrl:1
	ds_read_b128 v[38:41], v250 offset:1536
	s_nop 0
	v_mov_b32_dpp v61, v60 quad_perm:[1,0,3,2] row_mask:0xf bank_mask:0xf bound_ctrl:1
	v_pk_fma_f32 v[2:3], v[32:33], v[60:61], v[2:3] op_sel:[0,0,0] op_sel_hi:[0,1,1] neg_lo:[0,1,0] neg_hi:[0,1,0]
	v_pk_fma_f32 v[4:5], v[32:33], v[60:61], v[4:5] op_sel:[1,0,0] op_sel_hi:[1,1,1] neg_lo:[0,1,0] neg_hi:[0,1,0]
	v_pk_fma_f32 v[6:7], v[34:35], v[60:61], v[6:7] op_sel:[0,0,0] op_sel_hi:[0,1,1] neg_lo:[0,1,0] neg_hi:[0,1,0]
	v_pk_fma_f32 v[8:9], v[34:35], v[60:61], v[8:9] op_sel:[1,0,0] op_sel_hi:[1,1,1] neg_lo:[0,1,0] neg_hi:[0,1,0]
	v_pk_mul_f32 v[62:63], v[16:17], v[2:3] op_sel:[0,0] op_sel_hi:[0,1]
	ds_read_b128 v[28:31], v250 offset:3840
	v_pk_fma_f32 v[62:63], v[16:17], v[4:5], v[62:63] op_sel:[1,0,0] op_sel_hi:[1,1,1]
	ds_read_b32 v36, v251 offset:4352
	v_pk_fma_f32 v[62:63], v[18:19], v[6:7], v[62:63] op_sel:[0,0,0] op_sel_hi:[0,1,1]
	ds_read_b32 v37, v252 offset:4352
	v_pk_fma_f32 v[62:63], v[18:19], v[8:9], v[62:63] op_sel:[1,0,0] op_sel_hi:[1,1,1]
	ds_read_b128 v[24:27], v250 offset:3584
	ds_read_b128 v[20:23], v250 offset:3328
	s_waitcnt lgkmcnt(5)
	v_pk_mul_f32 v[60:61], v[50:51], v[2:3] op_sel:[0,0] op_sel_hi:[0,1]
	v_pk_mul_f32 v[64:65], v[46:47], v[58:59] op_sel:[0,0] op_sel_hi:[0,1]
	v_pk_fma_f32 v[60:61], v[50:51], v[4:5], v[60:61] op_sel:[1,0,0] op_sel_hi:[1,1,1]
	v_pk_mul_f32 v[14:15], v[46:47], v[58:59] op_sel:[1,0] op_sel_hi:[1,1]
	v_pk_fma_f32 v[60:61], v[52:53], v[6:7], v[60:61] op_sel:[0,0,0] op_sel_hi:[0,1,1]
	v_pk_fma_f32 v[2:3], v[42:43], v[2:3], v[64:65] op_sel:[0,0,0] op_sel_hi:[0,1,1]
	v_pk_fma_f32 v[60:61], v[52:53], v[8:9], v[60:61] op_sel:[1,0,0] op_sel_hi:[1,1,1]
	v_pk_fma_f32 v[4:5], v[42:43], v[4:5], v[14:15] op_sel:[1,0,0] op_sel_hi:[1,1,1]
	v_pk_mul_f32 v[64:65], v[48:49], v[58:59] op_sel:[0,0] op_sel_hi:[0,1]
	v_add_f32_dpp v60, v61, v60 quad_perm:[1,0,3,2] row_mask:0xf bank_mask:0xf bound_ctrl:1
	v_pk_mul_f32 v[14:15], v[48:49], v[58:59] op_sel:[1,0] op_sel_hi:[1,1]
	v_pk_fma_f32 v[6:7], v[44:45], v[6:7], v[64:65] op_sel:[0,0,0] op_sel_hi:[0,1,1]
	v_add_f32_dpp v60, v60, v60 quad_perm:[2,3,0,1] row_mask:0xf bank_mask:0xf bound_ctrl:1
	v_add_f32_dpp v62, v63, v62 quad_perm:[1,0,3,2] row_mask:0xf bank_mask:0xf bound_ctrl:1
	v_pk_fma_f32 v[8:9], v[44:45], v[8:9], v[14:15] op_sel:[1,0,0] op_sel_hi:[1,1,1]
	v_add_f32_dpp v60, v60, v60 row_half_mirror row_mask:0xf bank_mask:0xf bound_ctrl:1
	v_add_f32_dpp v62, v62, v62 quad_perm:[2,3,0,1] row_mask:0xf bank_mask:0xf bound_ctrl:1
	ds_read_b128 v[32:35], v250 offset:4096
	v_add_f32_dpp v60, v60, v60 row_mirror row_mask:0xf bank_mask:0xf bound_ctrl:1
	v_add_f32_dpp v62, v62, v62 row_half_mirror row_mask:0xf bank_mask:0xf bound_ctrl:1
	ds_read_b128 v[16:19], v250 offset:3072
	v_mov_b32_dpp v61, v60 quad_perm:[1,0,3,2] row_mask:0xf bank_mask:0xf bound_ctrl:1
	v_add_f32_dpp v62, v62, v62 row_mirror row_mask:0xf bank_mask:0xf bound_ctrl:1
	v_pk_fma_f32 v[2:3], v[54:55], v[60:61], v[2:3] op_sel:[0,0,0] op_sel_hi:[0,1,1] neg_lo:[0,1,0] neg_hi:[0,1,0]
	v_pk_fma_f32 v[4:5], v[54:55], v[60:61], v[4:5] op_sel:[1,0,0] op_sel_hi:[1,1,1] neg_lo:[0,1,0] neg_hi:[0,1,0]
	v_mov_b32_dpp v63, v62 quad_perm:[1,0,3,2] row_mask:0xf bank_mask:0xf bound_ctrl:1
	v_pk_fma_f32 v[6:7], v[56:57], v[60:61], v[6:7] op_sel:[0,0,0] op_sel_hi:[0,1,1] neg_lo:[0,1,0] neg_hi:[0,1,0]
	v_cvt_pk_bf16_f32 v64, v62, v63
	v_pk_fma_f32 v[8:9], v[56:57], v[60:61], v[8:9] op_sel:[1,0,0] op_sel_hi:[1,1,1] neg_lo:[0,1,0] neg_hi:[0,1,0]
	ds_write_b32 v253, v64 offset:0
	v_pk_mul_f32 v[62:63], v[38:39], v[2:3] op_sel:[0,0] op_sel_hi:[0,1]
	ds_read_b128 v[50:53], v250 offset:5376
	v_pk_fma_f32 v[62:63], v[38:39], v[4:5], v[62:63] op_sel:[1,0,0] op_sel_hi:[1,1,1]
	ds_read_b32 v58, v251 offset:5888
	v_pk_fma_f32 v[62:63], v[40:41], v[6:7], v[62:63] op_sel:[0,0,0] op_sel_hi:[0,1,1]
	ds_read_b32 v59, v252 offset:5888
	v_pk_fma_f32 v[62:63], v[40:41], v[8:9], v[62:63] op_sel:[1,0,0] op_sel_hi:[1,1,1]
	ds_read_b128 v[46:49], v250 offset:5120
	ds_read_b128 v[42:45], v250 offset:4864
	s_waitcnt lgkmcnt(5)
; #define LAS __attribute__((address_space(3)))
; DI unsigned pk2(float a, float b) { f32x2 v = {a, b}; bf2_t r = __builtin_convertvector(v, bf2_t); return __builtin_bit_cast(unsigned, r); }
; DI f32x2 red16p(f32x2 x) { float a = x.x, b = x.y; red16x2(a, b); return (f32x2){a, b}; }
; DI void scan_bh2(const Args& a, int l, int bh, int halfsel, LAS unsigned char* lds) {
;     ...
;             for (int st = 0; st < T; ++st) {
;                 f32x4 nr4, nd4, nk4, nkk4, nb4; f32x2 nv2;
;                 if (st < T - 1) {
;                     const LAS float* o = cur + (st + 1) * 384;
;                     nr4 = *(const LAS f32x4*)(o + kq * 4); nd4 = *(const LAS f32x4*)(o + 64 + kq * 4); nk4 = *(const LAS f32x4*)(o + 128 + kq * 4);
;                     nkk4 = *(const LAS f32x4*)(o + 192 + kq * 4); nb4 = *(const LAS f32x4*)(o + 256 + kq * 4); nv2 = *(const LAS f32x2*)(o + 320 + row0);
;                 }
;                 f32x2 sa = S[0] * kk4[0]; sa += S[1] * kk4[1]; f32x2 sb = S[2] * kk4[2]; sb += S[3] * kk4[3]; sa += sb;
;                 sa = red16p(sa); sa = -sa;
; #pragma unroll
;                 for (int j = 0; j < 4; ++j) S[j] = S[j] * d4[j] + sa * b4[j] + v2 * k4[j];
;                 f32x2 y = S[0] * r4[0]; y += S[1] * r4[1]; f32x2 yc = S[2] * r4[2]; yc += S[3] * r4[3]; y += yc;
;                 y = red16p(y);
;                 *(LAS unsigned*)(yb + st * 128 + row0 * 2) = pk2(y.x, y.y);
;                 if (st < T - 1) { r4 = nr4; d4 = nd4; k4 = nk4; kk4 = nkk4; b4 = nb4; v2 = nv2; }
	v_pk_mul_f32 v[60:61], v[28:29], v[2:3] op_sel:[0,0] op_sel_hi:[0,1]
	v_pk_mul_f32 v[64:65], v[24:25], v[36:37] op_sel:[0,0] op_sel_hi:[0,1]
	v_pk_fma_f32 v[60:61], v[28:29], v[4:5], v[60:61] op_sel:[1,0,0] op_sel_hi:[1,1,1]
	v_pk_mul_f32 v[14:15], v[24:25], v[36:37] op_sel:[1,0] op_sel_hi:[1,1]
	v_pk_fma_f32 v[60:61], v[30:31], v[6:7], v[60:61] op_sel:[0,0,0] op_sel_hi:[0,1,1]
	v_pk_fma_f32 v[2:3], v[20:21], v[2:3], v[64:65] op_sel:[0,0,0] op_sel_hi:[0,1,1]
	v_pk_fma_f32 v[60:61], v[30:31], v[8:9], v[60:61] op_sel:[1,0,0] op_sel_hi:[1,1,1]
	v_pk_fma_f32 v[4:5], v[20:21], v[4:5], v[14:15] op_sel:[1,0,0] op_sel_hi:[1,1,1]
	v_pk_mul_f32 v[64:65], v[26:27], v[36:37] op_sel:[0,0] op_sel_hi:[0,1]
	v_add_f32_dpp v60, v61, v60 quad_perm:[1,0,3,2] row_mask:0xf bank_mask:0xf bound_ctrl:1
	v_pk_mul_f32 v[14:15], v[26:27], v[36:37] op_sel:[1,0] op_sel_hi:[1,1]
	v_pk_fma_f32 v[6:7], v[22:23], v[6:7], v[64:65] op_sel:[0,0,0] op_sel_hi:[0,1,1]
	v_add_f32_dpp v60, v60, v60 quad_perm:[2,3,0,1] row_mask:0xf bank_mask:0xf bound_ctrl:1
	v_add_f32_dpp v62, v63, v62 quad_perm:[1,0,3,2] row_mask:0xf bank_mask:0xf bound_ctrl:1
	v_pk_fma_f32 v[8:9], v[22:23], v[8:9], v[14:15] op_sel:[1,0,0] op_sel_hi:[1,1,1]
	v_add_f32_dpp v60, v60, v60 row_half_mirror row_mask:0xf bank_mask:0xf bound_ctrl:1
	v_add_f32_dpp v62, v62, v62 quad_perm:[2,3,0,1] row_mask:0xf bank_mask:0xf bound_ctrl:1
	ds_read_b128 v[54:57], v250 offset:5632
	v_add_f32_dpp v60, v60, v60 row_mirror row_mask:0xf bank_mask:0xf bound_ctrl:1
	v_add_f32_dpp v62, v62, v62 row_half_mirror row_mask:0xf bank_mask:0xf bound_ctrl:1
	ds_read_b128 v[38:41], v250 offset:4608
	v_mov_b32_dpp v61, v60 quad_perm:[1,0,3,2] row_mask:0xf bank_mask:0xf bound_ctrl:1
	v_add_f32_dpp v62, v62, v62 row_mirror row_mask:0xf bank_mask:0xf bound_ctrl:1
	v_pk_fma_f32 v[2:3], v[32:33], v[60:61], v[2:3] op_sel:[0,0,0] op_sel_hi:[0,1,1] neg_lo:[0,1,0] neg_hi:[0,1,0]
	v_pk_fma_f32 v[4:5], v[32:33], v[60:61], v[4:5] op_sel:[1,0,0] op_sel_hi:[1,1,1] neg_lo:[0,1,0] neg_hi:[0,1,0]
	v_mov_b32_dpp v63, v62 quad_perm:[1,0,3,2] row_mask:0xf bank_mask:0xf bound_ctrl:1
	v_pk_fma_f32 v[6:7], v[34:35], v[60:61], v[6:7] op_sel:[0,0,0] op_sel_hi:[0,1,1] neg_lo:[0,1,0] neg_hi:[0,1,0]
	v_cvt_pk_bf16_f32 v64, v62, v63
	v_pk_fma_f32 v[8:9], v[34:35], v[60:61], v[8:9] op_sel:[1,0,0] op_sel_hi:[1,1,1] neg_lo:[0,1,0] neg_hi:[0,1,0]
	ds_write_b32 v253, v64 offset:128
	v_pk_mul_f32 v[62:63], v[16:17], v[2:3] op_sel:[0,0] op_sel_hi:[0,1]
	ds_read_b128 v[28:31], v250 offset:6912
	v_pk_fma_f32 v[62:63], v[16:17], v[4:5], v[62:63] op_sel:[1,0,0] op_sel_hi:[1,1,1]
	ds_read_b32 v36, v251 offset:7424
	v_pk_fma_f32 v[62:63], v[18:19], v[6:7], v[62:63] op_sel:[0,0,0] op_sel_hi:[0,1,1]
	ds_read_b32 v37, v252 offset:7424
	v_pk_fma_f32 v[62:63], v[18:19], v[8:9], v[62:63] op_sel:[1,0,0] op_sel_hi:[1,1,1]
	ds_read_b128 v[24:27], v250 offset:6656
	ds_read_b128 v[20:23], v250 offset:6400
	s_waitcnt lgkmcnt(5)
	v_pk_mul_f32 v[60:61], v[50:51], v[2:3] op_sel:[0,0] op_sel_hi:[0,1]
	v_pk_mul_f32 v[64:65], v[46:47], v[58:59] op_sel:[0,0] op_sel_hi:[0,1]
	v_pk_fma_f32 v[60:61], v[50:51], v[4:5], v[60:61] op_sel:[1,0,0] op_sel_hi:[1,1,1]
	v_pk_mul_f32 v[14:15], v[46:47], v[58:59] op_sel:[1,0] op_sel_hi:[1,1]
	v_pk_fma_f32 v[60:61], v[52:53], v[6:7], v[60:61] op_sel:[0,0,0] op_sel_hi:[0,1,1]
	v_pk_fma_f32 v[2:3], v[42:43], v[2:3], v[64:65] op_sel:[0,0,0] op_sel_hi:[0,1,1]
	v_pk_fma_f32 v[60:61], v[52:53], v[8:9], v[60:61] op_sel:[1,0,0] op_sel_hi:[1,1,1]
	v_pk_fma_f32 v[4:5], v[42:43], v[4:5], v[14:15] op_sel:[1,0,0] op_sel_hi:[1,1,1]
	v_pk_mul_f32 v[64:65], v[48:49], v[58:59] op_sel:[0,0] op_sel_hi:[0,1]
	v_add_f32_dpp v60, v61, v60 quad_perm:[1,0,3,2] row_mask:0xf bank_mask:0xf bound_ctrl:1
	v_pk_mul_f32 v[14:15], v[48:49], v[58:59] op_sel:[1,0] op_sel_hi:[1,1]
	v_pk_fma_f32 v[6:7], v[44:45], v[6:7], v[64:65] op_sel:[0,0,0] op_sel_hi:[0,1,1]
	v_add_f32_dpp v60, v60, v60 quad_perm:[2,3,0,1] row_mask:0xf bank_mask:0xf bound_ctrl:1
	v_add_f32_dpp v62, v63, v62 quad_perm:[1,0,3,2] row_mask:0xf bank_mask:0xf bound_ctrl:1
	v_pk_fma_f32 v[8:9], v[44:45], v[8:9], v[14:15] op_sel:[1,0,0] op_sel_hi:[1,1,1]
	v_add_f32_dpp v60, v60, v60 row_half_mirror row_mask:0xf bank_mask:0xf bound_ctrl:1
	v_add_f32_dpp v62, v62, v62 quad_perm:[2,3,0,1] row_mask:0xf bank_mask:0xf bound_ctrl:1
	ds_read_b128 v[32:35], v250 offset:7168
	v_add_f32_dpp v60, v60, v60 row_mirror row_mask:0xf bank_mask:0xf bound_ctrl:1
	v_add_f32_dpp v62, v62, v62 row_half_mirror row_mask:0xf bank_mask:0xf bound_ctrl:1
	ds_read_b128 v[16:19], v250 offset:6144
	v_mov_b32_dpp v61, v60 quad_perm:[1,0,3,2] row_mask:0xf bank_mask:0xf bound_ctrl:1
	v_add_f32_dpp v62, v62, v62 row_mirror row_mask:0xf bank_mask:0xf bound_ctrl:1
	v_pk_fma_f32 v[2:3], v[54:55], v[60:61], v[2:3] op_sel:[0,0,0] op_sel_hi:[0,1,1] neg_lo:[0,1,0] neg_hi:[0,1,0]
	v_pk_fma_f32 v[4:5], v[54:55], v[60:61], v[4:5] op_sel:[1,0,0] op_sel_hi:[1,1,1] neg_lo:[0,1,0] neg_hi:[0,1,0]
	v_mov_b32_dpp v63, v62 quad_perm:[1,0,3,2] row_mask:0xf bank_mask:0xf bound_ctrl:1
	v_pk_fma_f32 v[6:7], v[56:57], v[60:61], v[6:7] op_sel:[0,0,0] op_sel_hi:[0,1,1] neg_lo:[0,1,0] neg_hi:[0,1,0]
	v_cvt_pk_bf16_f32 v64, v62, v63
	v_pk_fma_f32 v[8:9], v[56:57], v[60:61], v[8:9] op_sel:[1,0,0] op_sel_hi:[1,1,1] neg_lo:[0,1,0] neg_hi:[0,1,0]
	ds_write_b32 v253, v64 offset:256
	v_pk_mul_f32 v[62:63], v[38:39], v[2:3] op_sel:[0,0] op_sel_hi:[0,1]
	ds_read_b128 v[50:53], v250 offset:8448
	v_pk_fma_f32 v[62:63], v[38:39], v[4:5], v[62:63] op_sel:[1,0,0] op_sel_hi:[1,1,1]
	ds_read_b32 v58, v251 offset:8960
	v_pk_fma_f32 v[62:63], v[40:41], v[6:7], v[62:63] op_sel:[0,0,0] op_sel_hi:[0,1,1]
	ds_read_b32 v59, v252 offset:8960
	v_pk_fma_f32 v[62:63], v[40:41], v[8:9], v[62:63] op_sel:[1,0,0] op_sel_hi:[1,1,1]
	ds_read_b128 v[46:49], v250 offset:8192
	ds_read_b128 v[42:45], v250 offset:7936
	s_waitcnt lgkmcnt(5)
; DI f32x2 red16p(f32x2 x) { float a = x.x, b = x.y; red16x2(a, b); return (f32x2){a, b}; }
; DI void scan_bh2(const Args& a, int l, int bh, int halfsel, LAS unsigned char* lds) {
;     ...
;                 f32x2 sa = S[0] * kk4[0]; sa += S[1] * kk4[1]; f32x2 sb = S[2] * kk4[2]; sb += S[3] * kk4[3]; sa += sb;
;                 sa = red16p(sa); sa = -sa;
; #pragma unroll
;                 for (int j = 0; j < 4; ++j) S[j] = S[j] * d4[j] + sa * b4[j] + v2 * k4[j];
	v_pk_mul_f32 v[60:61], v[28:29], v[2:3] op_sel:[0,0] op_sel_hi:[0,1]
	v_pk_mul_f32 v[64:65], v[24:25], v[36:37] op_sel:[0,0] op_sel_hi:[0,1]
	v_pk_fma_f32 v[60:61], v[28:29], v[4:5], v[60:61] op_sel:[1,0,0] op_sel_hi:[1,1,1]
	v_pk_mul_f32 v[14:15], v[24:25], v[36:37] op_sel:[1,0] op_sel_hi:[1,1]
	v_pk_fma_f32 v[60:61], v[30:31], v[6:7], v[60:61] op_sel:[0,0,0] op_sel_hi:[0,1,1]
	v_pk_fma_f32 v[2:3], v[20:21], v[2:3], v[64:65] op_sel:[0,0,0] op_sel_hi:[0,1,1]
	v_pk_fma_f32 v[60:61], v[30:31], v[8:9], v[60:61] op_sel:[1,0,0] op_sel_hi:[1,1,1]
	v_pk_fma_f32 v[4:5], v[20:21], v[4:5], v[14:15] op_sel:[1,0,0] op_sel_hi:[1,1,1]
	v_pk_mul_f32 v[64:65], v[26:27], v[36:37] op_sel:[0,0] op_sel_hi:[0,1]
	v_add_f32_dpp v60, v61, v60 quad_perm:[1,0,3,2] row_mask:0xf bank_mask:0xf bound_ctrl:1
	v_pk_mul_f32 v[14:15], v[26:27], v[36:37] op_sel:[1,0] op_sel_hi:[1,1]
	v_pk_fma_f32 v[6:7], v[22:23], v[6:7], v[64:65] op_sel:[0,0,0] op_sel_hi:[0,1,1]
	v_add_f32_dpp v60, v60, v60 quad_perm:[2,3,0,1] row_mask:0xf bank_mask:0xf bound_ctrl:1
	v_add_f32_dpp v62, v63, v62 quad_perm:[1,0,3,2] row_mask:0xf bank_mask:0xf bound_ctrl:1
	v_pk_fma_f32 v[8:9], v[22:23], v[8:9], v[14:15] op_sel:[1,0,0] op_sel_hi:[1,1,1]
	v_add_f32_dpp v60, v60, v60 row_half_mirror row_mask:0xf bank_mask:0xf bound_ctrl:1
	v_add_f32_dpp v62, v62, v62 quad_perm:[2,3,0,1] row_mask:0xf bank_mask:0xf bound_ctrl:1
	ds_read_b128 v[54:57], v250 offset:8704
	v_add_f32_dpp v60, v60, v60 row_mirror row_mask:0xf bank_mask:0xf bound_ctrl:1
	v_add_f32_dpp v62, v62, v62 row_half_mirror row_mask:0xf bank_mask:0xf bound_ctrl:1
	ds_read_b128 v[38:41], v250 offset:7680
	v_mov_b32_dpp v61, v60 quad_perm:[1,0,3,2] row_mask:0xf bank_mask:0xf bound_ctrl:1
	v_add_f32_dpp v62, v62, v62 row_mirror row_mask:0xf bank_mask:0xf bound_ctrl:1
	v_pk_fma_f32 v[2:3], v[32:33], v[60:61], v[2:3] op_sel:[0,0,0] op_sel_hi:[0,1,1] neg_lo:[0,1,0] neg_hi:[0,1,0]
	v_pk_fma_f32 v[4:5], v[32:33], v[60:61], v[4:5] op_sel:[1,0,0] op_sel_hi:[1,1,1] neg_lo:[0,1,0] neg_hi:[0,1,0]
	v_mov_b32_dpp v63, v62 quad_perm:[1,0,3,2] row_mask:0xf bank_mask:0xf bound_ctrl:1
	v_pk_fma_f32 v[6:7], v[34:35], v[60:61], v[6:7] op_sel:[0,0,0] op_sel_hi:[0,1,1] neg_lo:[0,1,0] neg_hi:[0,1,0]
	v_cvt_pk_bf16_f32 v64, v62, v63
	v_pk_fma_f32 v[8:9], v[34:35], v[60:61], v[8:9] op_sel:[1,0,0] op_sel_hi:[1,1,1] neg_lo:[0,1,0] neg_hi:[0,1,0]
	ds_write_b32 v253, v64 offset:384
	v_pk_mul_f32 v[62:63], v[16:17], v[2:3] op_sel:[0,0] op_sel_hi:[0,1]
	ds_read_b128 v[28:31], v250 offset:9984
	v_pk_fma_f32 v[62:63], v[16:17], v[4:5], v[62:63] op_sel:[1,0,0] op_sel_hi:[1,1,1]
	ds_read_b32 v36, v251 offset:10496
	v_pk_fma_f32 v[62:63], v[18:19], v[6:7], v[62:63] op_sel:[0,0,0] op_sel_hi:[0,1,1]
	ds_read_b32 v37, v252 offset:10496
	v_pk_fma_f32 v[62:63], v[18:19], v[8:9], v[62:63] op_sel:[1,0,0] op_sel_hi:[1,1,1]
	ds_read_b128 v[24:27], v250 offset:9728
	ds_read_b128 v[20:23], v250 offset:9472
	s_waitcnt lgkmcnt(5)
	v_pk_mul_f32 v[60:61], v[50:51], v[2:3] op_sel:[0,0] op_sel_hi:[0,1]
	v_pk_mul_f32 v[64:65], v[46:47], v[58:59] op_sel:[0,0] op_sel_hi:[0,1]
	v_pk_fma_f32 v[60:61], v[50:51], v[4:5], v[60:61] op_sel:[1,0,0] op_sel_hi:[1,1,1]
	v_pk_mul_f32 v[14:15], v[46:47], v[58:59] op_sel:[1,0] op_sel_hi:[1,1]
	v_pk_fma_f32 v[60:61], v[52:53], v[6:7], v[60:61] op_sel:[0,0,0] op_sel_hi:[0,1,1]
	v_pk_fma_f32 v[2:3], v[42:43], v[2:3], v[64:65] op_sel:[0,0,0] op_sel_hi:[0,1,1]
	v_pk_fma_f32 v[60:61], v[52:53], v[8:9], v[60:61] op_sel:[1,0,0] op_sel_hi:[1,1,1]
	v_pk_fma_f32 v[4:5], v[42:43], v[4:5], v[14:15] op_sel:[1,0,0] op_sel_hi:[1,1,1]
	v_pk_mul_f32 v[64:65], v[48:49], v[58:59] op_sel:[0,0] op_sel_hi:[0,1]
	v_add_f32_dpp v60, v61, v60 quad_perm:[1,0,3,2] row_mask:0xf bank_mask:0xf bound_ctrl:1
	v_pk_mul_f32 v[14:15], v[48:49], v[58:59] op_sel:[1,0] op_sel_hi:[1,1]
	v_pk_fma_f32 v[6:7], v[44:45], v[6:7], v[64:65] op_sel:[0,0,0] op_sel_hi:[0,1,1]
	v_add_f32_dpp v60, v60, v60 quad_perm:[2,3,0,1] row_mask:0xf bank_mask:0xf bound_ctrl:1
	v_add_f32_dpp v62, v63, v62 quad_perm:[1,0,3,2] row_mask:0xf bank_mask:0xf bound_ctrl:1
	v_pk_fma_f32 v[8:9], v[44:45], v[8:9], v[14:15] op_sel:[1,0,0] op_sel_hi:[1,1,1]
	v_add_f32_dpp v60, v60, v60 row_half_mirror row_mask:0xf bank_mask:0xf bound_ctrl:1
	v_add_f32_dpp v62, v62, v62 quad_perm:[2,3,0,1] row_mask:0xf bank_mask:0xf bound_ctrl:1
	ds_read_b128 v[32:35], v250 offset:10240
	v_add_f32_dpp v60, v60, v60 row_mirror row_mask:0xf bank_mask:0xf bound_ctrl:1
	v_add_f32_dpp v62, v62, v62 row_half_mirror row_mask:0xf bank_mask:0xf bound_ctrl:1
	ds_read_b128 v[16:19], v250 offset:9216
	v_mov_b32_dpp v61, v60 quad_perm:[1,0,3,2] row_mask:0xf bank_mask:0xf bound_ctrl:1
	v_add_f32_dpp v62, v62, v62 row_mirror row_mask:0xf bank_mask:0xf bound_ctrl:1
	v_pk_fma_f32 v[2:3], v[54:55], v[60:61], v[2:3] op_sel:[0,0,0] op_sel_hi:[0,1,1] neg_lo:[0,1,0] neg_hi:[0,1,0]
	v_pk_fma_f32 v[4:5], v[54:55], v[60:61], v[4:5] op_sel:[1,0,0] op_sel_hi:[1,1,1] neg_lo:[0,1,0] neg_hi:[0,1,0]
	v_mov_b32_dpp v63, v62 quad_perm:[1,0,3,2] row_mask:0xf bank_mask:0xf bound_ctrl:1
	v_pk_fma_f32 v[6:7], v[56:57], v[60:61], v[6:7] op_sel:[0,0,0] op_sel_hi:[0,1,1] neg_lo:[0,1,0] neg_hi:[0,1,0]
	v_cvt_pk_bf16_f32 v64, v62, v63
	v_pk_fma_f32 v[8:9], v[56:57], v[60:61], v[8:9] op_sel:[1,0,0] op_sel_hi:[1,1,1] neg_lo:[0,1,0] neg_hi:[0,1,0]
	ds_write_b32 v253, v64 offset:512
	v_pk_mul_f32 v[62:63], v[38:39], v[2:3] op_sel:[0,0] op_sel_hi:[0,1]
	ds_read_b128 v[50:53], v250 offset:11520
	v_pk_fma_f32 v[62:63], v[38:39], v[4:5], v[62:63] op_sel:[1,0,0] op_sel_hi:[1,1,1]
	ds_read_b32 v58, v251 offset:12032
	v_pk_fma_f32 v[62:63], v[40:41], v[6:7], v[62:63] op_sel:[0,0,0] op_sel_hi:[0,1,1]
	ds_read_b32 v59, v252 offset:12032
	v_pk_fma_f32 v[62:63], v[40:41], v[8:9], v[62:63] op_sel:[1,0,0] op_sel_hi:[1,1,1]
	ds_read_b128 v[46:49], v250 offset:11264
	ds_read_b128 v[42:45], v250 offset:11008
	s_waitcnt lgkmcnt(5)
; #define LAS __attribute__((address_space(3)))
; DI unsigned pk2(float a, float b) { f32x2 v = {a, b}; bf2_t r = __builtin_convertvector(v, bf2_t); return __builtin_bit_cast(unsigned, r); }
; DI void scan_bh2(const Args& a, int l, int bh, int halfsel, LAS unsigned char* lds) {
;     ...
;                 *(LAS unsigned*)(yb + st * 128 + row0 * 2) = pk2(y.x, y.y);
	v_pk_mul_f32 v[60:61], v[28:29], v[2:3] op_sel:[0,0] op_sel_hi:[0,1]
	v_pk_mul_f32 v[64:65], v[24:25], v[36:37] op_sel:[0,0] op_sel_hi:[0,1]
	v_pk_fma_f32 v[60:61], v[28:29], v[4:5], v[60:61] op_sel:[1,0,0] op_sel_hi:[1,1,1]
	v_pk_mul_f32 v[14:15], v[24:25], v[36:37] op_sel:[1,0] op_sel_hi:[1,1]
	v_pk_fma_f32 v[60:61], v[30:31], v[6:7], v[60:61] op_sel:[0,0,0] op_sel_hi:[0,1,1]
	v_pk_fma_f32 v[2:3], v[20:21], v[2:3], v[64:65] op_sel:[0,0,0] op_sel_hi:[0,1,1]
	v_pk_fma_f32 v[60:61], v[30:31], v[8:9], v[60:61] op_sel:[1,0,0] op_sel_hi:[1,1,1]
	v_pk_fma_f32 v[4:5], v[20:21], v[4:5], v[14:15] op_sel:[1,0,0] op_sel_hi:[1,1,1]
	v_pk_mul_f32 v[64:65], v[26:27], v[36:37] op_sel:[0,0] op_sel_hi:[0,1]
	v_add_f32_dpp v60, v61, v60 quad_perm:[1,0,3,2] row_mask:0xf bank_mask:0xf bound_ctrl:1
	v_pk_mul_f32 v[14:15], v[26:27], v[36:37] op_sel:[1,0] op_sel_hi:[1,1]
	v_pk_fma_f32 v[6:7], v[22:23], v[6:7], v[64:65] op_sel:[0,0,0] op_sel_hi:[0,1,1]
	v_add_f32_dpp v60, v60, v60 quad_perm:[2,3,0,1] row_mask:0xf bank_mask:0xf bound_ctrl:1
	v_add_f32_dpp v62, v63, v62 quad_perm:[1,0,3,2] row_mask:0xf bank_mask:0xf bound_ctrl:1
	v_pk_fma_f32 v[8:9], v[22:23], v[8:9], v[14:15] op_sel:[1,0,0] op_sel_hi:[1,1,1]
	v_add_f32_dpp v60, v60, v60 row_half_mirror row_mask:0xf bank_mask:0xf bound_ctrl:1
	v_add_f32_dpp v62, v62, v62 quad_perm:[2,3,0,1] row_mask:0xf bank_mask:0xf bound_ctrl:1
	ds_read_b128 v[54:57], v250 offset:11776
	v_add_f32_dpp v60, v60, v60 row_mirror row_mask:0xf bank_mask:0xf bound_ctrl:1
	v_add_f32_dpp v62, v62, v62 row_half_mirror row_mask:0xf bank_mask:0xf bound_ctrl:1
	ds_read_b128 v[38:41], v250 offset:10752
	v_mov_b32_dpp v61, v60 quad_perm:[1,0,3,2] row_mask:0xf bank_mask:0xf bound_ctrl:1
	v_add_f32_dpp v62, v62, v62 row_mirror row_mask:0xf bank_mask:0xf bound_ctrl:1
	v_pk_fma_f32 v[2:3], v[32:33], v[60:61], v[2:3] op_sel:[0,0,0] op_sel_hi:[0,1,1] neg_lo:[0,1,0] neg_hi:[0,1,0]
	v_pk_fma_f32 v[4:5], v[32:33], v[60:61], v[4:5] op_sel:[1,0,0] op_sel_hi:[1,1,1] neg_lo:[0,1,0] neg_hi:[0,1,0]
	v_mov_b32_dpp v63, v62 quad_perm:[1,0,3,2] row_mask:0xf bank_mask:0xf bound_ctrl:1
	v_pk_fma_f32 v[6:7], v[34:35], v[60:61], v[6:7] op_sel:[0,0,0] op_sel_hi:[0,1,1] neg_lo:[0,1,0] neg_hi:[0,1,0]
	v_cvt_pk_bf16_f32 v64, v62, v63
	v_pk_fma_f32 v[8:9], v[34:35], v[60:61], v[8:9] op_sel:[1,0,0] op_sel_hi:[1,1,1] neg_lo:[0,1,0] neg_hi:[0,1,0]
	ds_write_b32 v253, v64 offset:640
	v_pk_mul_f32 v[62:63], v[16:17], v[2:3] op_sel:[0,0] op_sel_hi:[0,1]
	ds_read_b128 v[28:31], v250 offset:13056
	v_pk_fma_f32 v[62:63], v[16:17], v[4:5], v[62:63] op_sel:[1,0,0] op_sel_hi:[1,1,1]
	ds_read_b32 v36, v251 offset:13568
	v_pk_fma_f32 v[62:63], v[18:19], v[6:7], v[62:63] op_sel:[0,0,0] op_sel_hi:[0,1,1]
	ds_read_b32 v37, v252 offset:13568
	v_pk_fma_f32 v[62:63], v[18:19], v[8:9], v[62:63] op_sel:[1,0,0] op_sel_hi:[1,1,1]
	ds_read_b128 v[24:27], v250 offset:12800
	ds_read_b128 v[20:23], v250 offset:12544
	s_waitcnt lgkmcnt(5)
	v_pk_mul_f32 v[60:61], v[50:51], v[2:3] op_sel:[0,0] op_sel_hi:[0,1]
	v_pk_mul_f32 v[64:65], v[46:47], v[58:59] op_sel:[0,0] op_sel_hi:[0,1]
	v_pk_fma_f32 v[60:61], v[50:51], v[4:5], v[60:61] op_sel:[1,0,0] op_sel_hi:[1,1,1]
	v_pk_mul_f32 v[14:15], v[46:47], v[58:59] op_sel:[1,0] op_sel_hi:[1,1]
	v_pk_fma_f32 v[60:61], v[52:53], v[6:7], v[60:61] op_sel:[0,0,0] op_sel_hi:[0,1,1]
	v_pk_fma_f32 v[2:3], v[42:43], v[2:3], v[64:65] op_sel:[0,0,0] op_sel_hi:[0,1,1]
	v_pk_fma_f32 v[60:61], v[52:53], v[8:9], v[60:61] op_sel:[1,0,0] op_sel_hi:[1,1,1]
	v_pk_fma_f32 v[4:5], v[42:43], v[4:5], v[14:15] op_sel:[1,0,0] op_sel_hi:[1,1,1]
	v_pk_mul_f32 v[64:65], v[48:49], v[58:59] op_sel:[0,0] op_sel_hi:[0,1]
	v_add_f32_dpp v60, v61, v60 quad_perm:[1,0,3,2] row_mask:0xf bank_mask:0xf bound_ctrl:1
	v_pk_mul_f32 v[14:15], v[48:49], v[58:59] op_sel:[1,0] op_sel_hi:[1,1]
	v_pk_fma_f32 v[6:7], v[44:45], v[6:7], v[64:65] op_sel:[0,0,0] op_sel_hi:[0,1,1]
	v_add_f32_dpp v60, v60, v60 quad_perm:[2,3,0,1] row_mask:0xf bank_mask:0xf bound_ctrl:1
	v_add_f32_dpp v62, v63, v62 quad_perm:[1,0,3,2] row_mask:0xf bank_mask:0xf bound_ctrl:1
	v_pk_fma_f32 v[8:9], v[44:45], v[8:9], v[14:15] op_sel:[1,0,0] op_sel_hi:[1,1,1]
	v_add_f32_dpp v60, v60, v60 row_half_mirror row_mask:0xf bank_mask:0xf bound_ctrl:1
	v_add_f32_dpp v62, v62, v62 quad_perm:[2,3,0,1] row_mask:0xf bank_mask:0xf bound_ctrl:1
	ds_read_b128 v[32:35], v250 offset:13312
	v_add_f32_dpp v60, v60, v60 row_mirror row_mask:0xf bank_mask:0xf bound_ctrl:1
	v_add_f32_dpp v62, v62, v62 row_half_mirror row_mask:0xf bank_mask:0xf bound_ctrl:1
	ds_read_b128 v[16:19], v250 offset:12288
	v_mov_b32_dpp v61, v60 quad_perm:[1,0,3,2] row_mask:0xf bank_mask:0xf bound_ctrl:1
	v_add_f32_dpp v62, v62, v62 row_mirror row_mask:0xf bank_mask:0xf bound_ctrl:1
	v_pk_fma_f32 v[2:3], v[54:55], v[60:61], v[2:3] op_sel:[0,0,0] op_sel_hi:[0,1,1] neg_lo:[0,1,0] neg_hi:[0,1,0]
	v_pk_fma_f32 v[4:5], v[54:55], v[60:61], v[4:5] op_sel:[1,0,0] op_sel_hi:[1,1,1] neg_lo:[0,1,0] neg_hi:[0,1,0]
	v_mov_b32_dpp v63, v62 quad_perm:[1,0,3,2] row_mask:0xf bank_mask:0xf bound_ctrl:1
	v_pk_fma_f32 v[6:7], v[56:57], v[60:61], v[6:7] op_sel:[0,0,0] op_sel_hi:[0,1,1] neg_lo:[0,1,0] neg_hi:[0,1,0]
	v_cvt_pk_bf16_f32 v64, v62, v63
	v_pk_fma_f32 v[8:9], v[56:57], v[60:61], v[8:9] op_sel:[1,0,0] op_sel_hi:[1,1,1] neg_lo:[0,1,0] neg_hi:[0,1,0]
	ds_write_b32 v253, v64 offset:768
	v_pk_mul_f32 v[62:63], v[38:39], v[2:3] op_sel:[0,0] op_sel_hi:[0,1]
	ds_read_b128 v[50:53], v250 offset:14592
	v_pk_fma_f32 v[62:63], v[38:39], v[4:5], v[62:63] op_sel:[1,0,0] op_sel_hi:[1,1,1]
	ds_read_b32 v58, v251 offset:15104
	v_pk_fma_f32 v[62:63], v[40:41], v[6:7], v[62:63] op_sel:[0,0,0] op_sel_hi:[0,1,1]
	ds_read_b32 v59, v252 offset:15104
	v_pk_fma_f32 v[62:63], v[40:41], v[8:9], v[62:63] op_sel:[1,0,0] op_sel_hi:[1,1,1]
	ds_read_b128 v[46:49], v250 offset:14336
	ds_read_b128 v[42:45], v250 offset:14080
	s_waitcnt lgkmcnt(5)
; #define LAS __attribute__((address_space(3)))
; DI void scan_bh2(const Args& a, int l, int bh, int halfsel, LAS unsigned char* lds) {
;     ...
;                 if (st < T - 1) {
;                     const LAS float* o = cur + (st + 1) * 384;
;                     nr4 = *(const LAS f32x4*)(o + kq * 4); nd4 = *(const LAS f32x4*)(o + 64 + kq * 4); nk4 = *(const LAS f32x4*)(o + 128 + kq * 4);
;                     nkk4 = *(const LAS f32x4*)(o + 192 + kq * 4); nb4 = *(const LAS f32x4*)(o + 256 + kq * 4); nv2 = *(const LAS f32x2*)(o + 320 + row0);
;                 }
	v_pk_mul_f32 v[60:61], v[28:29], v[2:3] op_sel:[0,0] op_sel_hi:[0,1]
	v_pk_mul_f32 v[64:65], v[24:25], v[36:37] op_sel:[0,0] op_sel_hi:[0,1]
	v_pk_fma_f32 v[60:61], v[28:29], v[4:5], v[60:61] op_sel:[1,0,0] op_sel_hi:[1,1,1]
	v_pk_mul_f32 v[14:15], v[24:25], v[36:37] op_sel:[1,0] op_sel_hi:[1,1]
	v_pk_fma_f32 v[60:61], v[30:31], v[6:7], v[60:61] op_sel:[0,0,0] op_sel_hi:[0,1,1]
	v_pk_fma_f32 v[2:3], v[20:21], v[2:3], v[64:65] op_sel:[0,0,0] op_sel_hi:[0,1,1]
	v_pk_fma_f32 v[60:61], v[30:31], v[8:9], v[60:61] op_sel:[1,0,0] op_sel_hi:[1,1,1]
	v_pk_fma_f32 v[4:5], v[20:21], v[4:5], v[14:15] op_sel:[1,0,0] op_sel_hi:[1,1,1]
	v_pk_mul_f32 v[64:65], v[26:27], v[36:37] op_sel:[0,0] op_sel_hi:[0,1]
	v_add_f32_dpp v60, v61, v60 quad_perm:[1,0,3,2] row_mask:0xf bank_mask:0xf bound_ctrl:1
	v_pk_mul_f32 v[14:15], v[26:27], v[36:37] op_sel:[1,0] op_sel_hi:[1,1]
	v_pk_fma_f32 v[6:7], v[22:23], v[6:7], v[64:65] op_sel:[0,0,0] op_sel_hi:[0,1,1]
	v_add_f32_dpp v60, v60, v60 quad_perm:[2,3,0,1] row_mask:0xf bank_mask:0xf bound_ctrl:1
	v_add_f32_dpp v62, v63, v62 quad_perm:[1,0,3,2] row_mask:0xf bank_mask:0xf bound_ctrl:1
	v_pk_fma_f32 v[8:9], v[22:23], v[8:9], v[14:15] op_sel:[1,0,0] op_sel_hi:[1,1,1]
	v_add_f32_dpp v60, v60, v60 row_half_mirror row_mask:0xf bank_mask:0xf bound_ctrl:1
	v_add_f32_dpp v62, v62, v62 quad_perm:[2,3,0,1] row_mask:0xf bank_mask:0xf bound_ctrl:1
	ds_read_b128 v[54:57], v250 offset:14848
	v_add_f32_dpp v60, v60, v60 row_mirror row_mask:0xf bank_mask:0xf bound_ctrl:1
	v_add_f32_dpp v62, v62, v62 row_half_mirror row_mask:0xf bank_mask:0xf bound_ctrl:1
	ds_read_b128 v[38:41], v250 offset:13824
	v_mov_b32_dpp v61, v60 quad_perm:[1,0,3,2] row_mask:0xf bank_mask:0xf bound_ctrl:1
	v_add_f32_dpp v62, v62, v62 row_mirror row_mask:0xf bank_mask:0xf bound_ctrl:1
	v_pk_fma_f32 v[2:3], v[32:33], v[60:61], v[2:3] op_sel:[0,0,0] op_sel_hi:[0,1,1] neg_lo:[0,1,0] neg_hi:[0,1,0]
	v_pk_fma_f32 v[4:5], v[32:33], v[60:61], v[4:5] op_sel:[1,0,0] op_sel_hi:[1,1,1] neg_lo:[0,1,0] neg_hi:[0,1,0]
	v_mov_b32_dpp v63, v62 quad_perm:[1,0,3,2] row_mask:0xf bank_mask:0xf bound_ctrl:1
	v_pk_fma_f32 v[6:7], v[34:35], v[60:61], v[6:7] op_sel:[0,0,0] op_sel_hi:[0,1,1] neg_lo:[0,1,0] neg_hi:[0,1,0]
	v_cvt_pk_bf16_f32 v64, v62, v63
	v_pk_fma_f32 v[8:9], v[34:35], v[60:61], v[8:9] op_sel:[1,0,0] op_sel_hi:[1,1,1] neg_lo:[0,1,0] neg_hi:[0,1,0]
	ds_write_b32 v253, v64 offset:896
	v_pk_mul_f32 v[62:63], v[16:17], v[2:3] op_sel:[0,0] op_sel_hi:[0,1]
	ds_read_b128 v[28:31], v250 offset:16128
	v_pk_fma_f32 v[62:63], v[16:17], v[4:5], v[62:63] op_sel:[1,0,0] op_sel_hi:[1,1,1]
	ds_read_b32 v36, v251 offset:16640
	v_pk_fma_f32 v[62:63], v[18:19], v[6:7], v[62:63] op_sel:[0,0,0] op_sel_hi:[0,1,1]
	ds_read_b32 v37, v252 offset:16640
	v_pk_fma_f32 v[62:63], v[18:19], v[8:9], v[62:63] op_sel:[1,0,0] op_sel_hi:[1,1,1]
	ds_read_b128 v[24:27], v250 offset:15872
	ds_read_b128 v[20:23], v250 offset:15616
	s_waitcnt lgkmcnt(5)
	v_pk_mul_f32 v[60:61], v[50:51], v[2:3] op_sel:[0,0] op_sel_hi:[0,1]
	v_pk_mul_f32 v[64:65], v[46:47], v[58:59] op_sel:[0,0] op_sel_hi:[0,1]
	v_pk_fma_f32 v[60:61], v[50:51], v[4:5], v[60:61] op_sel:[1,0,0] op_sel_hi:[1,1,1]
	v_pk_mul_f32 v[14:15], v[46:47], v[58:59] op_sel:[1,0] op_sel_hi:[1,1]
	v_pk_fma_f32 v[60:61], v[52:53], v[6:7], v[60:61] op_sel:[0,0,0] op_sel_hi:[0,1,1]
	v_pk_fma_f32 v[2:3], v[42:43], v[2:3], v[64:65] op_sel:[0,0,0] op_sel_hi:[0,1,1]
	v_pk_fma_f32 v[60:61], v[52:53], v[8:9], v[60:61] op_sel:[1,0,0] op_sel_hi:[1,1,1]
	v_pk_fma_f32 v[4:5], v[42:43], v[4:5], v[14:15] op_sel:[1,0,0] op_sel_hi:[1,1,1]
	v_pk_mul_f32 v[64:65], v[48:49], v[58:59] op_sel:[0,0] op_sel_hi:[0,1]
	v_add_f32_dpp v60, v61, v60 quad_perm:[1,0,3,2] row_mask:0xf bank_mask:0xf bound_ctrl:1
	v_pk_mul_f32 v[14:15], v[48:49], v[58:59] op_sel:[1,0] op_sel_hi:[1,1]
	v_pk_fma_f32 v[6:7], v[44:45], v[6:7], v[64:65] op_sel:[0,0,0] op_sel_hi:[0,1,1]
	v_add_f32_dpp v60, v60, v60 quad_perm:[2,3,0,1] row_mask:0xf bank_mask:0xf bound_ctrl:1
	v_add_f32_dpp v62, v63, v62 quad_perm:[1,0,3,2] row_mask:0xf bank_mask:0xf bound_ctrl:1
	v_pk_fma_f32 v[8:9], v[44:45], v[8:9], v[14:15] op_sel:[1,0,0] op_sel_hi:[1,1,1]
	v_add_f32_dpp v60, v60, v60 row_half_mirror row_mask:0xf bank_mask:0xf bound_ctrl:1
	v_add_f32_dpp v62, v62, v62 quad_perm:[2,3,0,1] row_mask:0xf bank_mask:0xf bound_ctrl:1
	ds_read_b128 v[32:35], v250 offset:16384
	v_add_f32_dpp v60, v60, v60 row_mirror row_mask:0xf bank_mask:0xf bound_ctrl:1
	v_add_f32_dpp v62, v62, v62 row_half_mirror row_mask:0xf bank_mask:0xf bound_ctrl:1
	ds_read_b128 v[16:19], v250 offset:15360
	v_mov_b32_dpp v61, v60 quad_perm:[1,0,3,2] row_mask:0xf bank_mask:0xf bound_ctrl:1
	v_add_f32_dpp v62, v62, v62 row_mirror row_mask:0xf bank_mask:0xf bound_ctrl:1
	v_pk_fma_f32 v[2:3], v[54:55], v[60:61], v[2:3] op_sel:[0,0,0] op_sel_hi:[0,1,1] neg_lo:[0,1,0] neg_hi:[0,1,0]
	v_pk_fma_f32 v[4:5], v[54:55], v[60:61], v[4:5] op_sel:[1,0,0] op_sel_hi:[1,1,1] neg_lo:[0,1,0] neg_hi:[0,1,0]
	v_mov_b32_dpp v63, v62 quad_perm:[1,0,3,2] row_mask:0xf bank_mask:0xf bound_ctrl:1
	v_pk_fma_f32 v[6:7], v[56:57], v[60:61], v[6:7] op_sel:[0,0,0] op_sel_hi:[0,1,1] neg_lo:[0,1,0] neg_hi:[0,1,0]
	v_cvt_pk_bf16_f32 v64, v62, v63
	v_pk_fma_f32 v[8:9], v[56:57], v[60:61], v[8:9] op_sel:[1,0,0] op_sel_hi:[1,1,1] neg_lo:[0,1,0] neg_hi:[0,1,0]
	ds_write_b32 v253, v64 offset:1024
	v_pk_mul_f32 v[62:63], v[38:39], v[2:3] op_sel:[0,0] op_sel_hi:[0,1]
	ds_read_b128 v[50:53], v250 offset:17664
	v_pk_fma_f32 v[62:63], v[38:39], v[4:5], v[62:63] op_sel:[1,0,0] op_sel_hi:[1,1,1]
	ds_read_b32 v58, v251 offset:18176
	v_pk_fma_f32 v[62:63], v[40:41], v[6:7], v[62:63] op_sel:[0,0,0] op_sel_hi:[0,1,1]
	ds_read_b32 v59, v252 offset:18176
	v_pk_fma_f32 v[62:63], v[40:41], v[8:9], v[62:63] op_sel:[1,0,0] op_sel_hi:[1,1,1]
	ds_read_b128 v[46:49], v250 offset:17408
	ds_read_b128 v[42:45], v250 offset:17152
	s_waitcnt lgkmcnt(5)
; #define LAS __attribute__((address_space(3)))
; DI unsigned pk2(float a, float b) { f32x2 v = {a, b}; bf2_t r = __builtin_convertvector(v, bf2_t); return __builtin_bit_cast(unsigned, r); }
; DI f32x2 red16p(f32x2 x) { float a = x.x, b = x.y; red16x2(a, b); return (f32x2){a, b}; }
; DI void scan_bh2(const Args& a, int l, int bh, int halfsel, LAS unsigned char* lds) {
;     ...
;                 f32x2 sa = S[0] * kk4[0]; sa += S[1] * kk4[1]; f32x2 sb = S[2] * kk4[2]; sb += S[3] * kk4[3]; sa += sb;
;                 sa = red16p(sa); sa = -sa;
; #pragma unroll
;                 for (int j = 0; j < 4; ++j) S[j] = S[j] * d4[j] + sa * b4[j] + v2 * k4[j];
;                 f32x2 y = S[0] * r4[0]; y += S[1] * r4[1]; f32x2 yc = S[2] * r4[2]; yc += S[3] * r4[3]; y += yc;
;                 y = red16p(y);
;                 *(LAS unsigned*)(yb + st * 128 + row0 * 2) = pk2(y.x, y.y);
	v_pk_mul_f32 v[60:61], v[28:29], v[2:3] op_sel:[0,0] op_sel_hi:[0,1]
	v_pk_mul_f32 v[64:65], v[24:25], v[36:37] op_sel:[0,0] op_sel_hi:[0,1]
	v_pk_fma_f32 v[60:61], v[28:29], v[4:5], v[60:61] op_sel:[1,0,0] op_sel_hi:[1,1,1]
	v_pk_mul_f32 v[14:15], v[24:25], v[36:37] op_sel:[1,0] op_sel_hi:[1,1]
	v_pk_fma_f32 v[60:61], v[30:31], v[6:7], v[60:61] op_sel:[0,0,0] op_sel_hi:[0,1,1]
	v_pk_fma_f32 v[2:3], v[20:21], v[2:3], v[64:65] op_sel:[0,0,0] op_sel_hi:[0,1,1]
	v_pk_fma_f32 v[60:61], v[30:31], v[8:9], v[60:61] op_sel:[1,0,0] op_sel_hi:[1,1,1]
	v_pk_fma_f32 v[4:5], v[20:21], v[4:5], v[14:15] op_sel:[1,0,0] op_sel_hi:[1,1,1]
	v_pk_mul_f32 v[64:65], v[26:27], v[36:37] op_sel:[0,0] op_sel_hi:[0,1]
	v_add_f32_dpp v60, v61, v60 quad_perm:[1,0,3,2] row_mask:0xf bank_mask:0xf bound_ctrl:1
	v_pk_mul_f32 v[14:15], v[26:27], v[36:37] op_sel:[1,0] op_sel_hi:[1,1]
	v_pk_fma_f32 v[6:7], v[22:23], v[6:7], v[64:65] op_sel:[0,0,0] op_sel_hi:[0,1,1]
	v_add_f32_dpp v60, v60, v60 quad_perm:[2,3,0,1] row_mask:0xf bank_mask:0xf bound_ctrl:1
	v_add_f32_dpp v62, v63, v62 quad_perm:[1,0,3,2] row_mask:0xf bank_mask:0xf bound_ctrl:1
	v_pk_fma_f32 v[8:9], v[22:23], v[8:9], v[14:15] op_sel:[1,0,0] op_sel_hi:[1,1,1]
	v_add_f32_dpp v60, v60, v60 row_half_mirror row_mask:0xf bank_mask:0xf bound_ctrl:1
	v_add_f32_dpp v62, v62, v62 quad_perm:[2,3,0,1] row_mask:0xf bank_mask:0xf bound_ctrl:1
	ds_read_b128 v[54:57], v250 offset:17920
	v_add_f32_dpp v60, v60, v60 row_mirror row_mask:0xf bank_mask:0xf bound_ctrl:1
	v_add_f32_dpp v62, v62, v62 row_half_mirror row_mask:0xf bank_mask:0xf bound_ctrl:1
	ds_read_b128 v[38:41], v250 offset:16896
	v_mov_b32_dpp v61, v60 quad_perm:[1,0,3,2] row_mask:0xf bank_mask:0xf bound_ctrl:1
	v_add_f32_dpp v62, v62, v62 row_mirror row_mask:0xf bank_mask:0xf bound_ctrl:1
	v_pk_fma_f32 v[2:3], v[32:33], v[60:61], v[2:3] op_sel:[0,0,0] op_sel_hi:[0,1,1] neg_lo:[0,1,0] neg_hi:[0,1,0]
	v_pk_fma_f32 v[4:5], v[32:33], v[60:61], v[4:5] op_sel:[1,0,0] op_sel_hi:[1,1,1] neg_lo:[0,1,0] neg_hi:[0,1,0]
	v_mov_b32_dpp v63, v62 quad_perm:[1,0,3,2] row_mask:0xf bank_mask:0xf bound_ctrl:1
	v_pk_fma_f32 v[6:7], v[34:35], v[60:61], v[6:7] op_sel:[0,0,0] op_sel_hi:[0,1,1] neg_lo:[0,1,0] neg_hi:[0,1,0]
	v_cvt_pk_bf16_f32 v64, v62, v63
	v_pk_fma_f32 v[8:9], v[34:35], v[60:61], v[8:9] op_sel:[1,0,0] op_sel_hi:[1,1,1] neg_lo:[0,1,0] neg_hi:[0,1,0]
	ds_write_b32 v253, v64 offset:1152
	v_pk_mul_f32 v[62:63], v[16:17], v[2:3] op_sel:[0,0] op_sel_hi:[0,1]
	ds_read_b128 v[28:31], v250 offset:19200
	v_pk_fma_f32 v[62:63], v[16:17], v[4:5], v[62:63] op_sel:[1,0,0] op_sel_hi:[1,1,1]
	ds_read_b32 v36, v251 offset:19712
	v_pk_fma_f32 v[62:63], v[18:19], v[6:7], v[62:63] op_sel:[0,0,0] op_sel_hi:[0,1,1]
	ds_read_b32 v37, v252 offset:19712
	v_pk_fma_f32 v[62:63], v[18:19], v[8:9], v[62:63] op_sel:[1,0,0] op_sel_hi:[1,1,1]
	ds_read_b128 v[24:27], v250 offset:18944
	ds_read_b128 v[20:23], v250 offset:18688
	s_waitcnt lgkmcnt(5)
	v_pk_mul_f32 v[60:61], v[50:51], v[2:3] op_sel:[0,0] op_sel_hi:[0,1]
	v_pk_mul_f32 v[64:65], v[46:47], v[58:59] op_sel:[0,0] op_sel_hi:[0,1]
	v_pk_fma_f32 v[60:61], v[50:51], v[4:5], v[60:61] op_sel:[1,0,0] op_sel_hi:[1,1,1]
	v_pk_mul_f32 v[14:15], v[46:47], v[58:59] op_sel:[1,0] op_sel_hi:[1,1]
	v_pk_fma_f32 v[60:61], v[52:53], v[6:7], v[60:61] op_sel:[0,0,0] op_sel_hi:[0,1,1]
	v_pk_fma_f32 v[2:3], v[42:43], v[2:3], v[64:65] op_sel:[0,0,0] op_sel_hi:[0,1,1]
	v_pk_fma_f32 v[60:61], v[52:53], v[8:9], v[60:61] op_sel:[1,0,0] op_sel_hi:[1,1,1]
	v_pk_fma_f32 v[4:5], v[42:43], v[4:5], v[14:15] op_sel:[1,0,0] op_sel_hi:[1,1,1]
	v_pk_mul_f32 v[64:65], v[48:49], v[58:59] op_sel:[0,0] op_sel_hi:[0,1]
	v_add_f32_dpp v60, v61, v60 quad_perm:[1,0,3,2] row_mask:0xf bank_mask:0xf bound_ctrl:1
	v_pk_mul_f32 v[14:15], v[48:49], v[58:59] op_sel:[1,0] op_sel_hi:[1,1]
	v_pk_fma_f32 v[6:7], v[44:45], v[6:7], v[64:65] op_sel:[0,0,0] op_sel_hi:[0,1,1]
	v_add_f32_dpp v60, v60, v60 quad_perm:[2,3,0,1] row_mask:0xf bank_mask:0xf bound_ctrl:1
	v_add_f32_dpp v62, v63, v62 quad_perm:[1,0,3,2] row_mask:0xf bank_mask:0xf bound_ctrl:1
	v_pk_fma_f32 v[8:9], v[44:45], v[8:9], v[14:15] op_sel:[1,0,0] op_sel_hi:[1,1,1]
	v_add_f32_dpp v60, v60, v60 row_half_mirror row_mask:0xf bank_mask:0xf bound_ctrl:1
	v_add_f32_dpp v62, v62, v62 quad_perm:[2,3,0,1] row_mask:0xf bank_mask:0xf bound_ctrl:1
	ds_read_b128 v[32:35], v250 offset:19456
	v_add_f32_dpp v60, v60, v60 row_mirror row_mask:0xf bank_mask:0xf bound_ctrl:1
	v_add_f32_dpp v62, v62, v62 row_half_mirror row_mask:0xf bank_mask:0xf bound_ctrl:1
	ds_read_b128 v[16:19], v250 offset:18432
	v_mov_b32_dpp v61, v60 quad_perm:[1,0,3,2] row_mask:0xf bank_mask:0xf bound_ctrl:1
	v_add_f32_dpp v62, v62, v62 row_mirror row_mask:0xf bank_mask:0xf bound_ctrl:1
	v_pk_fma_f32 v[2:3], v[54:55], v[60:61], v[2:3] op_sel:[0,0,0] op_sel_hi:[0,1,1] neg_lo:[0,1,0] neg_hi:[0,1,0]
	v_pk_fma_f32 v[4:5], v[54:55], v[60:61], v[4:5] op_sel:[1,0,0] op_sel_hi:[1,1,1] neg_lo:[0,1,0] neg_hi:[0,1,0]
	v_mov_b32_dpp v63, v62 quad_perm:[1,0,3,2] row_mask:0xf bank_mask:0xf bound_ctrl:1
	v_pk_fma_f32 v[6:7], v[56:57], v[60:61], v[6:7] op_sel:[0,0,0] op_sel_hi:[0,1,1] neg_lo:[0,1,0] neg_hi:[0,1,0]
	v_cvt_pk_bf16_f32 v64, v62, v63
	v_pk_fma_f32 v[8:9], v[56:57], v[60:61], v[8:9] op_sel:[1,0,0] op_sel_hi:[1,1,1] neg_lo:[0,1,0] neg_hi:[0,1,0]
	ds_write_b32 v253, v64 offset:1280
	v_pk_mul_f32 v[62:63], v[38:39], v[2:3] op_sel:[0,0] op_sel_hi:[0,1]
	ds_read_b128 v[50:53], v250 offset:20736
	v_pk_fma_f32 v[62:63], v[38:39], v[4:5], v[62:63] op_sel:[1,0,0] op_sel_hi:[1,1,1]
	ds_read_b32 v58, v251 offset:21248
	v_pk_fma_f32 v[62:63], v[40:41], v[6:7], v[62:63] op_sel:[0,0,0] op_sel_hi:[0,1,1]
	ds_read_b32 v59, v252 offset:21248
	v_pk_fma_f32 v[62:63], v[40:41], v[8:9], v[62:63] op_sel:[1,0,0] op_sel_hi:[1,1,1]
	ds_read_b128 v[46:49], v250 offset:20480
	ds_read_b128 v[42:45], v250 offset:20224
	s_waitcnt lgkmcnt(5)
; #define LAS __attribute__((address_space(3)))
; DI unsigned pk2(float a, float b) { f32x2 v = {a, b}; bf2_t r = __builtin_convertvector(v, bf2_t); return __builtin_bit_cast(unsigned, r); }
; DI f32x2 red16p(f32x2 x) { float a = x.x, b = x.y; red16x2(a, b); return (f32x2){a, b}; }
; DI void scan_bh2(const Args& a, int l, int bh, int halfsel, LAS unsigned char* lds) {
;     ...
;                 f32x2 sa = S[0] * kk4[0]; sa += S[1] * kk4[1]; f32x2 sb = S[2] * kk4[2]; sb += S[3] * kk4[3]; sa += sb;
;                 sa = red16p(sa); sa = -sa;
; #pragma unroll
;                 for (int j = 0; j < 4; ++j) S[j] = S[j] * d4[j] + sa * b4[j] + v2 * k4[j];
;                 f32x2 y = S[0] * r4[0]; y += S[1] * r4[1]; f32x2 yc = S[2] * r4[2]; yc += S[3] * r4[3]; y += yc;
;                 y = red16p(y);
;                 *(LAS unsigned*)(yb + st * 128 + row0 * 2) = pk2(y.x, y.y);
;                 if (st < T - 1) { r4 = nr4; d4 = nd4; k4 = nk4; kk4 = nkk4; b4 = nb4; v2 = nv2; }
	v_pk_mul_f32 v[60:61], v[28:29], v[2:3] op_sel:[0,0] op_sel_hi:[0,1]
	v_pk_mul_f32 v[64:65], v[24:25], v[36:37] op_sel:[0,0] op_sel_hi:[0,1]
	v_pk_fma_f32 v[60:61], v[28:29], v[4:5], v[60:61] op_sel:[1,0,0] op_sel_hi:[1,1,1]
	v_pk_mul_f32 v[14:15], v[24:25], v[36:37] op_sel:[1,0] op_sel_hi:[1,1]
	v_pk_fma_f32 v[60:61], v[30:31], v[6:7], v[60:61] op_sel:[0,0,0] op_sel_hi:[0,1,1]
	v_pk_fma_f32 v[2:3], v[20:21], v[2:3], v[64:65] op_sel:[0,0,0] op_sel_hi:[0,1,1]
	v_pk_fma_f32 v[60:61], v[30:31], v[8:9], v[60:61] op_sel:[1,0,0] op_sel_hi:[1,1,1]
	v_pk_fma_f32 v[4:5], v[20:21], v[4:5], v[14:15] op_sel:[1,0,0] op_sel_hi:[1,1,1]
	v_pk_mul_f32 v[64:65], v[26:27], v[36:37] op_sel:[0,0] op_sel_hi:[0,1]
	v_add_f32_dpp v60, v61, v60 quad_perm:[1,0,3,2] row_mask:0xf bank_mask:0xf bound_ctrl:1
	v_pk_mul_f32 v[14:15], v[26:27], v[36:37] op_sel:[1,0] op_sel_hi:[1,1]
	v_pk_fma_f32 v[6:7], v[22:23], v[6:7], v[64:65] op_sel:[0,0,0] op_sel_hi:[0,1,1]
	v_add_f32_dpp v60, v60, v60 quad_perm:[2,3,0,1] row_mask:0xf bank_mask:0xf bound_ctrl:1
	v_add_f32_dpp v62, v63, v62 quad_perm:[1,0,3,2] row_mask:0xf bank_mask:0xf bound_ctrl:1
	v_pk_fma_f32 v[8:9], v[22:23], v[8:9], v[14:15] op_sel:[1,0,0] op_sel_hi:[1,1,1]
	v_add_f32_dpp v60, v60, v60 row_half_mirror row_mask:0xf bank_mask:0xf bound_ctrl:1
	v_add_f32_dpp v62, v62, v62 quad_perm:[2,3,0,1] row_mask:0xf bank_mask:0xf bound_ctrl:1
	ds_read_b128 v[54:57], v250 offset:20992
	v_add_f32_dpp v60, v60, v60 row_mirror row_mask:0xf bank_mask:0xf bound_ctrl:1
	v_add_f32_dpp v62, v62, v62 row_half_mirror row_mask:0xf bank_mask:0xf bound_ctrl:1
	ds_read_b128 v[38:41], v250 offset:19968
	v_mov_b32_dpp v61, v60 quad_perm:[1,0,3,2] row_mask:0xf bank_mask:0xf bound_ctrl:1
	v_add_f32_dpp v62, v62, v62 row_mirror row_mask:0xf bank_mask:0xf bound_ctrl:1
	v_pk_fma_f32 v[2:3], v[32:33], v[60:61], v[2:3] op_sel:[0,0,0] op_sel_hi:[0,1,1] neg_lo:[0,1,0] neg_hi:[0,1,0]
	v_pk_fma_f32 v[4:5], v[32:33], v[60:61], v[4:5] op_sel:[1,0,0] op_sel_hi:[1,1,1] neg_lo:[0,1,0] neg_hi:[0,1,0]
	v_mov_b32_dpp v63, v62 quad_perm:[1,0,3,2] row_mask:0xf bank_mask:0xf bound_ctrl:1
	v_pk_fma_f32 v[6:7], v[34:35], v[60:61], v[6:7] op_sel:[0,0,0] op_sel_hi:[0,1,1] neg_lo:[0,1,0] neg_hi:[0,1,0]
	v_cvt_pk_bf16_f32 v64, v62, v63
	v_pk_fma_f32 v[8:9], v[34:35], v[60:61], v[8:9] op_sel:[1,0,0] op_sel_hi:[1,1,1] neg_lo:[0,1,0] neg_hi:[0,1,0]
	ds_write_b32 v253, v64 offset:1408
	v_pk_mul_f32 v[62:63], v[16:17], v[2:3] op_sel:[0,0] op_sel_hi:[0,1]
	ds_read_b128 v[28:31], v250 offset:22272
	v_pk_fma_f32 v[62:63], v[16:17], v[4:5], v[62:63] op_sel:[1,0,0] op_sel_hi:[1,1,1]
	ds_read_b32 v36, v251 offset:22784
	v_pk_fma_f32 v[62:63], v[18:19], v[6:7], v[62:63] op_sel:[0,0,0] op_sel_hi:[0,1,1]
	ds_read_b32 v37, v252 offset:22784
	v_pk_fma_f32 v[62:63], v[18:19], v[8:9], v[62:63] op_sel:[1,0,0] op_sel_hi:[1,1,1]
	ds_read_b128 v[24:27], v250 offset:22016
	ds_read_b128 v[20:23], v250 offset:21760
	s_waitcnt lgkmcnt(5)
	v_pk_mul_f32 v[60:61], v[50:51], v[2:3] op_sel:[0,0] op_sel_hi:[0,1]
	v_pk_mul_f32 v[64:65], v[46:47], v[58:59] op_sel:[0,0] op_sel_hi:[0,1]
	v_pk_fma_f32 v[60:61], v[50:51], v[4:5], v[60:61] op_sel:[1,0,0] op_sel_hi:[1,1,1]
	v_pk_mul_f32 v[14:15], v[46:47], v[58:59] op_sel:[1,0] op_sel_hi:[1,1]
	v_pk_fma_f32 v[60:61], v[52:53], v[6:7], v[60:61] op_sel:[0,0,0] op_sel_hi:[0,1,1]
	v_pk_fma_f32 v[2:3], v[42:43], v[2:3], v[64:65] op_sel:[0,0,0] op_sel_hi:[0,1,1]
	v_pk_fma_f32 v[60:61], v[52:53], v[8:9], v[60:61] op_sel:[1,0,0] op_sel_hi:[1,1,1]
	v_pk_fma_f32 v[4:5], v[42:43], v[4:5], v[14:15] op_sel:[1,0,0] op_sel_hi:[1,1,1]
	v_pk_mul_f32 v[64:65], v[48:49], v[58:59] op_sel:[0,0] op_sel_hi:[0,1]
	v_add_f32_dpp v60, v61, v60 quad_perm:[1,0,3,2] row_mask:0xf bank_mask:0xf bound_ctrl:1
	v_pk_mul_f32 v[14:15], v[48:49], v[58:59] op_sel:[1,0] op_sel_hi:[1,1]
	v_pk_fma_f32 v[6:7], v[44:45], v[6:7], v[64:65] op_sel:[0,0,0] op_sel_hi:[0,1,1]
	v_add_f32_dpp v60, v60, v60 quad_perm:[2,3,0,1] row_mask:0xf bank_mask:0xf bound_ctrl:1
	v_add_f32_dpp v62, v63, v62 quad_perm:[1,0,3,2] row_mask:0xf bank_mask:0xf bound_ctrl:1
	v_pk_fma_f32 v[8:9], v[44:45], v[8:9], v[14:15] op_sel:[1,0,0] op_sel_hi:[1,1,1]
	v_add_f32_dpp v60, v60, v60 row_half_mirror row_mask:0xf bank_mask:0xf bound_ctrl:1
	v_add_f32_dpp v62, v62, v62 quad_perm:[2,3,0,1] row_mask:0xf bank_mask:0xf bound_ctrl:1
	ds_read_b128 v[32:35], v250 offset:22528
	v_add_f32_dpp v60, v60, v60 row_mirror row_mask:0xf bank_mask:0xf bound_ctrl:1
	v_add_f32_dpp v62, v62, v62 row_half_mirror row_mask:0xf bank_mask:0xf bound_ctrl:1
	ds_read_b128 v[16:19], v250 offset:21504
	v_mov_b32_dpp v61, v60 quad_perm:[1,0,3,2] row_mask:0xf bank_mask:0xf bound_ctrl:1
	v_add_f32_dpp v62, v62, v62 row_mirror row_mask:0xf bank_mask:0xf bound_ctrl:1
	v_pk_fma_f32 v[2:3], v[54:55], v[60:61], v[2:3] op_sel:[0,0,0] op_sel_hi:[0,1,1] neg_lo:[0,1,0] neg_hi:[0,1,0]
	v_pk_fma_f32 v[4:5], v[54:55], v[60:61], v[4:5] op_sel:[1,0,0] op_sel_hi:[1,1,1] neg_lo:[0,1,0] neg_hi:[0,1,0]
	v_mov_b32_dpp v63, v62 quad_perm:[1,0,3,2] row_mask:0xf bank_mask:0xf bound_ctrl:1
	v_pk_fma_f32 v[6:7], v[56:57], v[60:61], v[6:7] op_sel:[0,0,0] op_sel_hi:[0,1,1] neg_lo:[0,1,0] neg_hi:[0,1,0]
	v_cvt_pk_bf16_f32 v64, v62, v63
	v_pk_fma_f32 v[8:9], v[56:57], v[60:61], v[8:9] op_sel:[1,0,0] op_sel_hi:[1,1,1] neg_lo:[0,1,0] neg_hi:[0,1,0]
	ds_write_b32 v253, v64 offset:1536
	v_pk_mul_f32 v[62:63], v[38:39], v[2:3] op_sel:[0,0] op_sel_hi:[0,1]
	ds_read_b128 v[50:53], v250 offset:23808
	v_pk_fma_f32 v[62:63], v[38:39], v[4:5], v[62:63] op_sel:[1,0,0] op_sel_hi:[1,1,1]
	ds_read_b32 v58, v251 offset:24320
	v_pk_fma_f32 v[62:63], v[40:41], v[6:7], v[62:63] op_sel:[0,0,0] op_sel_hi:[0,1,1]
	ds_read_b32 v59, v252 offset:24320
	v_pk_fma_f32 v[62:63], v[40:41], v[8:9], v[62:63] op_sel:[1,0,0] op_sel_hi:[1,1,1]
	ds_read_b128 v[46:49], v250 offset:23552
	ds_read_b128 v[42:45], v250 offset:23296
	s_waitcnt lgkmcnt(5)
; #define LAS __attribute__((address_space(3)))
; DI unsigned pk2(float a, float b) { f32x2 v = {a, b}; bf2_t r = __builtin_convertvector(v, bf2_t); return __builtin_bit_cast(unsigned, r); }
; DI f32x2 red16p(f32x2 x) { float a = x.x, b = x.y; red16x2(a, b); return (f32x2){a, b}; }
; DI void scan_bh2(const Args& a, int l, int bh, int halfsel, LAS unsigned char* lds) {
;     ...
;                 f32x2 sa = S[0] * kk4[0]; sa += S[1] * kk4[1]; f32x2 sb = S[2] * kk4[2]; sb += S[3] * kk4[3]; sa += sb;
;                 sa = red16p(sa); sa = -sa;
; #pragma unroll
;                 for (int j = 0; j < 4; ++j) S[j] = S[j] * d4[j] + sa * b4[j] + v2 * k4[j];
;                 f32x2 y = S[0] * r4[0]; y += S[1] * r4[1]; f32x2 yc = S[2] * r4[2]; yc += S[3] * r4[3]; y += yc;
;                 y = red16p(y);
;                 *(LAS unsigned*)(yb + st * 128 + row0 * 2) = pk2(y.x, y.y);
;                 if (st < T - 1) { r4 = nr4; d4 = nd4; k4 = nk4; kk4 = nkk4; b4 = nb4; v2 = nv2; }
	v_pk_mul_f32 v[60:61], v[28:29], v[2:3] op_sel:[0,0] op_sel_hi:[0,1]
	v_pk_mul_f32 v[64:65], v[24:25], v[36:37] op_sel:[0,0] op_sel_hi:[0,1]
	v_pk_fma_f32 v[60:61], v[28:29], v[4:5], v[60:61] op_sel:[1,0,0] op_sel_hi:[1,1,1]
	v_pk_mul_f32 v[14:15], v[24:25], v[36:37] op_sel:[1,0] op_sel_hi:[1,1]
	v_pk_fma_f32 v[60:61], v[30:31], v[6:7], v[60:61] op_sel:[0,0,0] op_sel_hi:[0,1,1]
	v_pk_fma_f32 v[2:3], v[20:21], v[2:3], v[64:65] op_sel:[0,0,0] op_sel_hi:[0,1,1]
	v_pk_fma_f32 v[60:61], v[30:31], v[8:9], v[60:61] op_sel:[1,0,0] op_sel_hi:[1,1,1]
	v_pk_fma_f32 v[4:5], v[20:21], v[4:5], v[14:15] op_sel:[1,0,0] op_sel_hi:[1,1,1]
	v_pk_mul_f32 v[64:65], v[26:27], v[36:37] op_sel:[0,0] op_sel_hi:[0,1]
	v_add_f32_dpp v60, v61, v60 quad_perm:[1,0,3,2] row_mask:0xf bank_mask:0xf bound_ctrl:1
	v_pk_mul_f32 v[14:15], v[26:27], v[36:37] op_sel:[1,0] op_sel_hi:[1,1]
	v_pk_fma_f32 v[6:7], v[22:23], v[6:7], v[64:65] op_sel:[0,0,0] op_sel_hi:[0,1,1]
	v_add_f32_dpp v60, v60, v60 quad_perm:[2,3,0,1] row_mask:0xf bank_mask:0xf bound_ctrl:1
	v_add_f32_dpp v62, v63, v62 quad_perm:[1,0,3,2] row_mask:0xf bank_mask:0xf bound_ctrl:1
	v_pk_fma_f32 v[8:9], v[22:23], v[8:9], v[14:15] op_sel:[1,0,0] op_sel_hi:[1,1,1]
	v_add_f32_dpp v60, v60, v60 row_half_mirror row_mask:0xf bank_mask:0xf bound_ctrl:1
	v_add_f32_dpp v62, v62, v62 quad_perm:[2,3,0,1] row_mask:0xf bank_mask:0xf bound_ctrl:1
	ds_read_b128 v[54:57], v250 offset:24064
	v_add_f32_dpp v60, v60, v60 row_mirror row_mask:0xf bank_mask:0xf bound_ctrl:1
	v_add_f32_dpp v62, v62, v62 row_half_mirror row_mask:0xf bank_mask:0xf bound_ctrl:1
	ds_read_b128 v[38:41], v250 offset:23040
	v_mov_b32_dpp v61, v60 quad_perm:[1,0,3,2] row_mask:0xf bank_mask:0xf bound_ctrl:1
	v_add_f32_dpp v62, v62, v62 row_mirror row_mask:0xf bank_mask:0xf bound_ctrl:1
	v_pk_fma_f32 v[2:3], v[32:33], v[60:61], v[2:3] op_sel:[0,0,0] op_sel_hi:[0,1,1] neg_lo:[0,1,0] neg_hi:[0,1,0]
	v_pk_fma_f32 v[4:5], v[32:33], v[60:61], v[4:5] op_sel:[1,0,0] op_sel_hi:[1,1,1] neg_lo:[0,1,0] neg_hi:[0,1,0]
	v_mov_b32_dpp v63, v62 quad_perm:[1,0,3,2] row_mask:0xf bank_mask:0xf bound_ctrl:1
	v_pk_fma_f32 v[6:7], v[34:35], v[60:61], v[6:7] op_sel:[0,0,0] op_sel_hi:[0,1,1] neg_lo:[0,1,0] neg_hi:[0,1,0]
	v_cvt_pk_bf16_f32 v64, v62, v63
	v_pk_fma_f32 v[8:9], v[34:35], v[60:61], v[8:9] op_sel:[1,0,0] op_sel_hi:[1,1,1] neg_lo:[0,1,0] neg_hi:[0,1,0]
	ds_write_b32 v253, v64 offset:1664
	v_pk_mul_f32 v[62:63], v[16:17], v[2:3] op_sel:[0,0] op_sel_hi:[0,1]
	ds_read_b128 v[28:31], v250 offset:25344
	v_pk_fma_f32 v[62:63], v[16:17], v[4:5], v[62:63] op_sel:[1,0,0] op_sel_hi:[1,1,1]
	ds_read_b32 v36, v251 offset:25856
	v_pk_fma_f32 v[62:63], v[18:19], v[6:7], v[62:63] op_sel:[0,0,0] op_sel_hi:[0,1,1]
	ds_read_b32 v37, v252 offset:25856
	v_pk_fma_f32 v[62:63], v[18:19], v[8:9], v[62:63] op_sel:[1,0,0] op_sel_hi:[1,1,1]
	ds_read_b128 v[24:27], v250 offset:25088
	ds_read_b128 v[20:23], v250 offset:24832
	s_waitcnt lgkmcnt(5)
	v_pk_mul_f32 v[60:61], v[50:51], v[2:3] op_sel:[0,0] op_sel_hi:[0,1]
	v_pk_mul_f32 v[64:65], v[46:47], v[58:59] op_sel:[0,0] op_sel_hi:[0,1]
	v_pk_fma_f32 v[60:61], v[50:51], v[4:5], v[60:61] op_sel:[1,0,0] op_sel_hi:[1,1,1]
	v_pk_mul_f32 v[14:15], v[46:47], v[58:59] op_sel:[1,0] op_sel_hi:[1,1]
	v_pk_fma_f32 v[60:61], v[52:53], v[6:7], v[60:61] op_sel:[0,0,0] op_sel_hi:[0,1,1]
	v_pk_fma_f32 v[2:3], v[42:43], v[2:3], v[64:65] op_sel:[0,0,0] op_sel_hi:[0,1,1]
	v_pk_fma_f32 v[60:61], v[52:53], v[8:9], v[60:61] op_sel:[1,0,0] op_sel_hi:[1,1,1]
	v_pk_fma_f32 v[4:5], v[42:43], v[4:5], v[14:15] op_sel:[1,0,0] op_sel_hi:[1,1,1]
	v_pk_mul_f32 v[64:65], v[48:49], v[58:59] op_sel:[0,0] op_sel_hi:[0,1]
	v_add_f32_dpp v60, v61, v60 quad_perm:[1,0,3,2] row_mask:0xf bank_mask:0xf bound_ctrl:1
	v_pk_mul_f32 v[14:15], v[48:49], v[58:59] op_sel:[1,0] op_sel_hi:[1,1]
	v_pk_fma_f32 v[6:7], v[44:45], v[6:7], v[64:65] op_sel:[0,0,0] op_sel_hi:[0,1,1]
	v_add_f32_dpp v60, v60, v60 quad_perm:[2,3,0,1] row_mask:0xf bank_mask:0xf bound_ctrl:1
	v_add_f32_dpp v62, v63, v62 quad_perm:[1,0,3,2] row_mask:0xf bank_mask:0xf bound_ctrl:1
	v_pk_fma_f32 v[8:9], v[44:45], v[8:9], v[14:15] op_sel:[1,0,0] op_sel_hi:[1,1,1]
	v_add_f32_dpp v60, v60, v60 row_half_mirror row_mask:0xf bank_mask:0xf bound_ctrl:1
	v_add_f32_dpp v62, v62, v62 quad_perm:[2,3,0,1] row_mask:0xf bank_mask:0xf bound_ctrl:1
	ds_read_b128 v[32:35], v250 offset:25600
	v_add_f32_dpp v60, v60, v60 row_mirror row_mask:0xf bank_mask:0xf bound_ctrl:1
	v_add_f32_dpp v62, v62, v62 row_half_mirror row_mask:0xf bank_mask:0xf bound_ctrl:1
	ds_read_b128 v[16:19], v250 offset:24576
	v_mov_b32_dpp v61, v60 quad_perm:[1,0,3,2] row_mask:0xf bank_mask:0xf bound_ctrl:1
	v_add_f32_dpp v62, v62, v62 row_mirror row_mask:0xf bank_mask:0xf bound_ctrl:1
	v_pk_fma_f32 v[2:3], v[54:55], v[60:61], v[2:3] op_sel:[0,0,0] op_sel_hi:[0,1,1] neg_lo:[0,1,0] neg_hi:[0,1,0]
	v_pk_fma_f32 v[4:5], v[54:55], v[60:61], v[4:5] op_sel:[1,0,0] op_sel_hi:[1,1,1] neg_lo:[0,1,0] neg_hi:[0,1,0]
	v_mov_b32_dpp v63, v62 quad_perm:[1,0,3,2] row_mask:0xf bank_mask:0xf bound_ctrl:1
	v_pk_fma_f32 v[6:7], v[56:57], v[60:61], v[6:7] op_sel:[0,0,0] op_sel_hi:[0,1,1] neg_lo:[0,1,0] neg_hi:[0,1,0]
	v_cvt_pk_bf16_f32 v64, v62, v63
	v_pk_fma_f32 v[8:9], v[56:57], v[60:61], v[8:9] op_sel:[1,0,0] op_sel_hi:[1,1,1] neg_lo:[0,1,0] neg_hi:[0,1,0]
	ds_write_b32 v253, v64 offset:1792
	v_pk_mul_f32 v[62:63], v[38:39], v[2:3] op_sel:[0,0] op_sel_hi:[0,1]
	ds_read_b128 v[50:53], v250 offset:26880
	v_pk_fma_f32 v[62:63], v[38:39], v[4:5], v[62:63] op_sel:[1,0,0] op_sel_hi:[1,1,1]
	ds_read_b32 v58, v251 offset:27392
	v_pk_fma_f32 v[62:63], v[40:41], v[6:7], v[62:63] op_sel:[0,0,0] op_sel_hi:[0,1,1]
	ds_read_b32 v59, v252 offset:27392
	v_pk_fma_f32 v[62:63], v[40:41], v[8:9], v[62:63] op_sel:[1,0,0] op_sel_hi:[1,1,1]
	ds_read_b128 v[46:49], v250 offset:26624
	ds_read_b128 v[42:45], v250 offset:26368
	s_waitcnt lgkmcnt(5)
; #define LAS __attribute__((address_space(3)))
; DI unsigned pk2(float a, float b) { f32x2 v = {a, b}; bf2_t r = __builtin_convertvector(v, bf2_t); return __builtin_bit_cast(unsigned, r); }
; DI f32x2 red16p(f32x2 x) { float a = x.x, b = x.y; red16x2(a, b); return (f32x2){a, b}; }
; DI void scan_bh2(const Args& a, int l, int bh, int halfsel, LAS unsigned char* lds) {
;     ...
;                 f32x2 sa = S[0] * kk4[0]; sa += S[1] * kk4[1]; f32x2 sb = S[2] * kk4[2]; sb += S[3] * kk4[3]; sa += sb;
;                 sa = red16p(sa); sa = -sa;
; #pragma unroll
;                 for (int j = 0; j < 4; ++j) S[j] = S[j] * d4[j] + sa * b4[j] + v2 * k4[j];
;                 f32x2 y = S[0] * r4[0]; y += S[1] * r4[1]; f32x2 yc = S[2] * r4[2]; yc += S[3] * r4[3]; y += yc;
;                 y = red16p(y);
;                 *(LAS unsigned*)(yb + st * 128 + row0 * 2) = pk2(y.x, y.y);
;                 if (st < T - 1) { r4 = nr4; d4 = nd4; k4 = nk4; kk4 = nkk4; b4 = nb4; v2 = nv2; }
	v_pk_mul_f32 v[60:61], v[28:29], v[2:3] op_sel:[0,0] op_sel_hi:[0,1]
	v_pk_mul_f32 v[64:65], v[24:25], v[36:37] op_sel:[0,0] op_sel_hi:[0,1]
	v_pk_fma_f32 v[60:61], v[28:29], v[4:5], v[60:61] op_sel:[1,0,0] op_sel_hi:[1,1,1]
	v_pk_mul_f32 v[14:15], v[24:25], v[36:37] op_sel:[1,0] op_sel_hi:[1,1]
	v_pk_fma_f32 v[60:61], v[30:31], v[6:7], v[60:61] op_sel:[0,0,0] op_sel_hi:[0,1,1]
	v_pk_fma_f32 v[2:3], v[20:21], v[2:3], v[64:65] op_sel:[0,0,0] op_sel_hi:[0,1,1]
	v_pk_fma_f32 v[60:61], v[30:31], v[8:9], v[60:61] op_sel:[1,0,0] op_sel_hi:[1,1,1]
	v_pk_fma_f32 v[4:5], v[20:21], v[4:5], v[14:15] op_sel:[1,0,0] op_sel_hi:[1,1,1]
	v_pk_mul_f32 v[64:65], v[26:27], v[36:37] op_sel:[0,0] op_sel_hi:[0,1]
	v_add_f32_dpp v60, v61, v60 quad_perm:[1,0,3,2] row_mask:0xf bank_mask:0xf bound_ctrl:1
	v_pk_mul_f32 v[14:15], v[26:27], v[36:37] op_sel:[1,0] op_sel_hi:[1,1]
	v_pk_fma_f32 v[6:7], v[22:23], v[6:7], v[64:65] op_sel:[0,0,0] op_sel_hi:[0,1,1]
	v_add_f32_dpp v60, v60, v60 quad_perm:[2,3,0,1] row_mask:0xf bank_mask:0xf bound_ctrl:1
	v_add_f32_dpp v62, v63, v62 quad_perm:[1,0,3,2] row_mask:0xf bank_mask:0xf bound_ctrl:1
	v_pk_fma_f32 v[8:9], v[22:23], v[8:9], v[14:15] op_sel:[1,0,0] op_sel_hi:[1,1,1]
	v_add_f32_dpp v60, v60, v60 row_half_mirror row_mask:0xf bank_mask:0xf bound_ctrl:1
	v_add_f32_dpp v62, v62, v62 quad_perm:[2,3,0,1] row_mask:0xf bank_mask:0xf bound_ctrl:1
	ds_read_b128 v[54:57], v250 offset:27136
	v_add_f32_dpp v60, v60, v60 row_mirror row_mask:0xf bank_mask:0xf bound_ctrl:1
	v_add_f32_dpp v62, v62, v62 row_half_mirror row_mask:0xf bank_mask:0xf bound_ctrl:1
	ds_read_b128 v[38:41], v250 offset:26112
	v_mov_b32_dpp v61, v60 quad_perm:[1,0,3,2] row_mask:0xf bank_mask:0xf bound_ctrl:1
	v_add_f32_dpp v62, v62, v62 row_mirror row_mask:0xf bank_mask:0xf bound_ctrl:1
	v_pk_fma_f32 v[2:3], v[32:33], v[60:61], v[2:3] op_sel:[0,0,0] op_sel_hi:[0,1,1] neg_lo:[0,1,0] neg_hi:[0,1,0]
	v_pk_fma_f32 v[4:5], v[32:33], v[60:61], v[4:5] op_sel:[1,0,0] op_sel_hi:[1,1,1] neg_lo:[0,1,0] neg_hi:[0,1,0]
	v_mov_b32_dpp v63, v62 quad_perm:[1,0,3,2] row_mask:0xf bank_mask:0xf bound_ctrl:1
	v_pk_fma_f32 v[6:7], v[34:35], v[60:61], v[6:7] op_sel:[0,0,0] op_sel_hi:[0,1,1] neg_lo:[0,1,0] neg_hi:[0,1,0]
	v_cvt_pk_bf16_f32 v64, v62, v63
	v_pk_fma_f32 v[8:9], v[34:35], v[60:61], v[8:9] op_sel:[1,0,0] op_sel_hi:[1,1,1] neg_lo:[0,1,0] neg_hi:[0,1,0]
	ds_write_b32 v253, v64 offset:1920
	v_pk_mul_f32 v[62:63], v[16:17], v[2:3] op_sel:[0,0] op_sel_hi:[0,1]
	ds_read_b128 v[28:31], v250 offset:28416
	v_pk_fma_f32 v[62:63], v[16:17], v[4:5], v[62:63] op_sel:[1,0,0] op_sel_hi:[1,1,1]
	ds_read_b32 v36, v251 offset:28928
	v_pk_fma_f32 v[62:63], v[18:19], v[6:7], v[62:63] op_sel:[0,0,0] op_sel_hi:[0,1,1]
	ds_read_b32 v37, v252 offset:28928
	v_pk_fma_f32 v[62:63], v[18:19], v[8:9], v[62:63] op_sel:[1,0,0] op_sel_hi:[1,1,1]
	ds_read_b128 v[24:27], v250 offset:28160
	ds_read_b128 v[20:23], v250 offset:27904
	s_waitcnt lgkmcnt(5)
	v_pk_mul_f32 v[60:61], v[50:51], v[2:3] op_sel:[0,0] op_sel_hi:[0,1]
	v_pk_mul_f32 v[64:65], v[46:47], v[58:59] op_sel:[0,0] op_sel_hi:[0,1]
	v_pk_fma_f32 v[60:61], v[50:51], v[4:5], v[60:61] op_sel:[1,0,0] op_sel_hi:[1,1,1]
	v_pk_mul_f32 v[14:15], v[46:47], v[58:59] op_sel:[1,0] op_sel_hi:[1,1]
	v_pk_fma_f32 v[60:61], v[52:53], v[6:7], v[60:61] op_sel:[0,0,0] op_sel_hi:[0,1,1]
	v_pk_fma_f32 v[2:3], v[42:43], v[2:3], v[64:65] op_sel:[0,0,0] op_sel_hi:[0,1,1]
	v_pk_fma_f32 v[60:61], v[52:53], v[8:9], v[60:61] op_sel:[1,0,0] op_sel_hi:[1,1,1]
	v_pk_fma_f32 v[4:5], v[42:43], v[4:5], v[14:15] op_sel:[1,0,0] op_sel_hi:[1,1,1]
	v_pk_mul_f32 v[64:65], v[48:49], v[58:59] op_sel:[0,0] op_sel_hi:[0,1]
	v_add_f32_dpp v60, v61, v60 quad_perm:[1,0,3,2] row_mask:0xf bank_mask:0xf bound_ctrl:1
	v_pk_mul_f32 v[14:15], v[48:49], v[58:59] op_sel:[1,0] op_sel_hi:[1,1]
	v_pk_fma_f32 v[6:7], v[44:45], v[6:7], v[64:65] op_sel:[0,0,0] op_sel_hi:[0,1,1]
	v_add_f32_dpp v60, v60, v60 quad_perm:[2,3,0,1] row_mask:0xf bank_mask:0xf bound_ctrl:1
	v_add_f32_dpp v62, v63, v62 quad_perm:[1,0,3,2] row_mask:0xf bank_mask:0xf bound_ctrl:1
	v_pk_fma_f32 v[8:9], v[44:45], v[8:9], v[14:15] op_sel:[1,0,0] op_sel_hi:[1,1,1]
	v_add_f32_dpp v60, v60, v60 row_half_mirror row_mask:0xf bank_mask:0xf bound_ctrl:1
	v_add_f32_dpp v62, v62, v62 quad_perm:[2,3,0,1] row_mask:0xf bank_mask:0xf bound_ctrl:1
	ds_read_b128 v[32:35], v250 offset:28672
	v_add_f32_dpp v60, v60, v60 row_mirror row_mask:0xf bank_mask:0xf bound_ctrl:1
	v_add_f32_dpp v62, v62, v62 row_half_mirror row_mask:0xf bank_mask:0xf bound_ctrl:1
	ds_read_b128 v[16:19], v250 offset:27648
	v_mov_b32_dpp v61, v60 quad_perm:[1,0,3,2] row_mask:0xf bank_mask:0xf bound_ctrl:1
	v_add_f32_dpp v62, v62, v62 row_mirror row_mask:0xf bank_mask:0xf bound_ctrl:1
	v_pk_fma_f32 v[2:3], v[54:55], v[60:61], v[2:3] op_sel:[0,0,0] op_sel_hi:[0,1,1] neg_lo:[0,1,0] neg_hi:[0,1,0]
	v_pk_fma_f32 v[4:5], v[54:55], v[60:61], v[4:5] op_sel:[1,0,0] op_sel_hi:[1,1,1] neg_lo:[0,1,0] neg_hi:[0,1,0]
	v_mov_b32_dpp v63, v62 quad_perm:[1,0,3,2] row_mask:0xf bank_mask:0xf bound_ctrl:1
	v_pk_fma_f32 v[6:7], v[56:57], v[60:61], v[6:7] op_sel:[0,0,0] op_sel_hi:[0,1,1] neg_lo:[0,1,0] neg_hi:[0,1,0]
	v_cvt_pk_bf16_f32 v64, v62, v63
	v_pk_fma_f32 v[8:9], v[56:57], v[60:61], v[8:9] op_sel:[1,0,0] op_sel_hi:[1,1,1] neg_lo:[0,1,0] neg_hi:[0,1,0]
	ds_write_b32 v253, v64 offset:2048
	v_pk_mul_f32 v[62:63], v[38:39], v[2:3] op_sel:[0,0] op_sel_hi:[0,1]
	ds_read_b128 v[50:53], v250 offset:29952
	v_pk_fma_f32 v[62:63], v[38:39], v[4:5], v[62:63] op_sel:[1,0,0] op_sel_hi:[1,1,1]
	ds_read_b32 v58, v251 offset:30464
	v_pk_fma_f32 v[62:63], v[40:41], v[6:7], v[62:63] op_sel:[0,0,0] op_sel_hi:[0,1,1]
	ds_read_b32 v59, v252 offset:30464
	v_pk_fma_f32 v[62:63], v[40:41], v[8:9], v[62:63] op_sel:[1,0,0] op_sel_hi:[1,1,1]
	ds_read_b128 v[46:49], v250 offset:29696
	ds_read_b128 v[42:45], v250 offset:29440
	s_waitcnt lgkmcnt(5)
; #define LAS __attribute__((address_space(3)))
; DI unsigned pk2(float a, float b) { f32x2 v = {a, b}; bf2_t r = __builtin_convertvector(v, bf2_t); return __builtin_bit_cast(unsigned, r); }
; DI f32x2 red16p(f32x2 x) { float a = x.x, b = x.y; red16x2(a, b); return (f32x2){a, b}; }
; DI void scan_bh2(const Args& a, int l, int bh, int halfsel, LAS unsigned char* lds) {
;     ...
;                 f32x2 sa = S[0] * kk4[0]; sa += S[1] * kk4[1]; f32x2 sb = S[2] * kk4[2]; sb += S[3] * kk4[3]; sa += sb;
;                 sa = red16p(sa); sa = -sa;
; #pragma unroll
;                 for (int j = 0; j < 4; ++j) S[j] = S[j] * d4[j] + sa * b4[j] + v2 * k4[j];
;                 f32x2 y = S[0] * r4[0]; y += S[1] * r4[1]; f32x2 yc = S[2] * r4[2]; yc += S[3] * r4[3]; y += yc;
;                 y = red16p(y);
;                 *(LAS unsigned*)(yb + st * 128 + row0 * 2) = pk2(y.x, y.y);
;                 if (st < T - 1) { r4 = nr4; d4 = nd4; k4 = nk4; kk4 = nkk4; b4 = nb4; v2 = nv2; }
	v_pk_mul_f32 v[60:61], v[28:29], v[2:3] op_sel:[0,0] op_sel_hi:[0,1]
	v_pk_mul_f32 v[64:65], v[24:25], v[36:37] op_sel:[0,0] op_sel_hi:[0,1]
	v_pk_fma_f32 v[60:61], v[28:29], v[4:5], v[60:61] op_sel:[1,0,0] op_sel_hi:[1,1,1]
	v_pk_mul_f32 v[14:15], v[24:25], v[36:37] op_sel:[1,0] op_sel_hi:[1,1]
	v_pk_fma_f32 v[60:61], v[30:31], v[6:7], v[60:61] op_sel:[0,0,0] op_sel_hi:[0,1,1]
	v_pk_fma_f32 v[2:3], v[20:21], v[2:3], v[64:65] op_sel:[0,0,0] op_sel_hi:[0,1,1]
	v_pk_fma_f32 v[60:61], v[30:31], v[8:9], v[60:61] op_sel:[1,0,0] op_sel_hi:[1,1,1]
	v_pk_fma_f32 v[4:5], v[20:21], v[4:5], v[14:15] op_sel:[1,0,0] op_sel_hi:[1,1,1]
	v_pk_mul_f32 v[64:65], v[26:27], v[36:37] op_sel:[0,0] op_sel_hi:[0,1]
	v_add_f32_dpp v60, v61, v60 quad_perm:[1,0,3,2] row_mask:0xf bank_mask:0xf bound_ctrl:1
	v_pk_mul_f32 v[14:15], v[26:27], v[36:37] op_sel:[1,0] op_sel_hi:[1,1]
	v_pk_fma_f32 v[6:7], v[22:23], v[6:7], v[64:65] op_sel:[0,0,0] op_sel_hi:[0,1,1]
	v_add_f32_dpp v60, v60, v60 quad_perm:[2,3,0,1] row_mask:0xf bank_mask:0xf bound_ctrl:1
	v_add_f32_dpp v62, v63, v62 quad_perm:[1,0,3,2] row_mask:0xf bank_mask:0xf bound_ctrl:1
	v_pk_fma_f32 v[8:9], v[22:23], v[8:9], v[14:15] op_sel:[1,0,0] op_sel_hi:[1,1,1]
	v_add_f32_dpp v60, v60, v60 row_half_mirror row_mask:0xf bank_mask:0xf bound_ctrl:1
	v_add_f32_dpp v62, v62, v62 quad_perm:[2,3,0,1] row_mask:0xf bank_mask:0xf bound_ctrl:1
	ds_read_b128 v[54:57], v250 offset:30208
	v_add_f32_dpp v60, v60, v60 row_mirror row_mask:0xf bank_mask:0xf bound_ctrl:1
	v_add_f32_dpp v62, v62, v62 row_half_mirror row_mask:0xf bank_mask:0xf bound_ctrl:1
	ds_read_b128 v[38:41], v250 offset:29184
	v_mov_b32_dpp v61, v60 quad_perm:[1,0,3,2] row_mask:0xf bank_mask:0xf bound_ctrl:1
	v_add_f32_dpp v62, v62, v62 row_mirror row_mask:0xf bank_mask:0xf bound_ctrl:1
	v_pk_fma_f32 v[2:3], v[32:33], v[60:61], v[2:3] op_sel:[0,0,0] op_sel_hi:[0,1,1] neg_lo:[0,1,0] neg_hi:[0,1,0]
	v_pk_fma_f32 v[4:5], v[32:33], v[60:61], v[4:5] op_sel:[1,0,0] op_sel_hi:[1,1,1] neg_lo:[0,1,0] neg_hi:[0,1,0]
	v_mov_b32_dpp v63, v62 quad_perm:[1,0,3,2] row_mask:0xf bank_mask:0xf bound_ctrl:1
	v_pk_fma_f32 v[6:7], v[34:35], v[60:61], v[6:7] op_sel:[0,0,0] op_sel_hi:[0,1,1] neg_lo:[0,1,0] neg_hi:[0,1,0]
	v_cvt_pk_bf16_f32 v64, v62, v63
	v_pk_fma_f32 v[8:9], v[34:35], v[60:61], v[8:9] op_sel:[1,0,0] op_sel_hi:[1,1,1] neg_lo:[0,1,0] neg_hi:[0,1,0]
	ds_write_b32 v253, v64 offset:2176
	v_pk_mul_f32 v[62:63], v[16:17], v[2:3] op_sel:[0,0] op_sel_hi:[0,1]
	ds_read_b128 v[28:31], v250 offset:31488
	v_pk_fma_f32 v[62:63], v[16:17], v[4:5], v[62:63] op_sel:[1,0,0] op_sel_hi:[1,1,1]
	ds_read_b32 v36, v251 offset:32000
	v_pk_fma_f32 v[62:63], v[18:19], v[6:7], v[62:63] op_sel:[0,0,0] op_sel_hi:[0,1,1]
	ds_read_b32 v37, v252 offset:32000
	v_pk_fma_f32 v[62:63], v[18:19], v[8:9], v[62:63] op_sel:[1,0,0] op_sel_hi:[1,1,1]
	ds_read_b128 v[24:27], v250 offset:31232
	ds_read_b128 v[20:23], v250 offset:30976
	s_waitcnt lgkmcnt(5)
	v_pk_mul_f32 v[60:61], v[50:51], v[2:3] op_sel:[0,0] op_sel_hi:[0,1]
	v_pk_mul_f32 v[64:65], v[46:47], v[58:59] op_sel:[0,0] op_sel_hi:[0,1]
	v_pk_fma_f32 v[60:61], v[50:51], v[4:5], v[60:61] op_sel:[1,0,0] op_sel_hi:[1,1,1]
	v_pk_mul_f32 v[14:15], v[46:47], v[58:59] op_sel:[1,0] op_sel_hi:[1,1]
	v_pk_fma_f32 v[60:61], v[52:53], v[6:7], v[60:61] op_sel:[0,0,0] op_sel_hi:[0,1,1]
	v_pk_fma_f32 v[2:3], v[42:43], v[2:3], v[64:65] op_sel:[0,0,0] op_sel_hi:[0,1,1]
	v_pk_fma_f32 v[60:61], v[52:53], v[8:9], v[60:61] op_sel:[1,0,0] op_sel_hi:[1,1,1]
	v_pk_fma_f32 v[4:5], v[42:43], v[4:5], v[14:15] op_sel:[1,0,0] op_sel_hi:[1,1,1]
	v_pk_mul_f32 v[64:65], v[48:49], v[58:59] op_sel:[0,0] op_sel_hi:[0,1]
	v_add_f32_dpp v60, v61, v60 quad_perm:[1,0,3,2] row_mask:0xf bank_mask:0xf bound_ctrl:1
	v_pk_mul_f32 v[14:15], v[48:49], v[58:59] op_sel:[1,0] op_sel_hi:[1,1]
	v_pk_fma_f32 v[6:7], v[44:45], v[6:7], v[64:65] op_sel:[0,0,0] op_sel_hi:[0,1,1]
	v_add_f32_dpp v60, v60, v60 quad_perm:[2,3,0,1] row_mask:0xf bank_mask:0xf bound_ctrl:1
	v_add_f32_dpp v62, v63, v62 quad_perm:[1,0,3,2] row_mask:0xf bank_mask:0xf bound_ctrl:1
	v_pk_fma_f32 v[8:9], v[44:45], v[8:9], v[14:15] op_sel:[1,0,0] op_sel_hi:[1,1,1]
	v_add_f32_dpp v60, v60, v60 row_half_mirror row_mask:0xf bank_mask:0xf bound_ctrl:1
	v_add_f32_dpp v62, v62, v62 quad_perm:[2,3,0,1] row_mask:0xf bank_mask:0xf bound_ctrl:1
	ds_read_b128 v[32:35], v250 offset:31744
	v_add_f32_dpp v60, v60, v60 row_mirror row_mask:0xf bank_mask:0xf bound_ctrl:1
	v_add_f32_dpp v62, v62, v62 row_half_mirror row_mask:0xf bank_mask:0xf bound_ctrl:1
	ds_read_b128 v[16:19], v250 offset:30720
	v_mov_b32_dpp v61, v60 quad_perm:[1,0,3,2] row_mask:0xf bank_mask:0xf bound_ctrl:1
	v_add_f32_dpp v62, v62, v62 row_mirror row_mask:0xf bank_mask:0xf bound_ctrl:1
	v_pk_fma_f32 v[2:3], v[54:55], v[60:61], v[2:3] op_sel:[0,0,0] op_sel_hi:[0,1,1] neg_lo:[0,1,0] neg_hi:[0,1,0]
	v_pk_fma_f32 v[4:5], v[54:55], v[60:61], v[4:5] op_sel:[1,0,0] op_sel_hi:[1,1,1] neg_lo:[0,1,0] neg_hi:[0,1,0]
	v_mov_b32_dpp v63, v62 quad_perm:[1,0,3,2] row_mask:0xf bank_mask:0xf bound_ctrl:1
	v_pk_fma_f32 v[6:7], v[56:57], v[60:61], v[6:7] op_sel:[0,0,0] op_sel_hi:[0,1,1] neg_lo:[0,1,0] neg_hi:[0,1,0]
	v_cvt_pk_bf16_f32 v64, v62, v63
	v_pk_fma_f32 v[8:9], v[56:57], v[60:61], v[8:9] op_sel:[1,0,0] op_sel_hi:[1,1,1] neg_lo:[0,1,0] neg_hi:[0,1,0]
	ds_write_b32 v253, v64 offset:2304
	v_pk_mul_f32 v[62:63], v[38:39], v[2:3] op_sel:[0,0] op_sel_hi:[0,1]
	ds_read_b128 v[50:53], v250 offset:33024
	v_pk_fma_f32 v[62:63], v[38:39], v[4:5], v[62:63] op_sel:[1,0,0] op_sel_hi:[1,1,1]
	ds_read_b32 v58, v251 offset:33536
	v_pk_fma_f32 v[62:63], v[40:41], v[6:7], v[62:63] op_sel:[0,0,0] op_sel_hi:[0,1,1]
	ds_read_b32 v59, v252 offset:33536
	v_pk_fma_f32 v[62:63], v[40:41], v[8:9], v[62:63] op_sel:[1,0,0] op_sel_hi:[1,1,1]
	ds_read_b128 v[46:49], v250 offset:32768
	ds_read_b128 v[42:45], v250 offset:32512
	s_waitcnt lgkmcnt(5)
; #define LAS __attribute__((address_space(3)))
; DI unsigned pk2(float a, float b) { f32x2 v = {a, b}; bf2_t r = __builtin_convertvector(v, bf2_t); return __builtin_bit_cast(unsigned, r); }
; DI f32x2 red16p(f32x2 x) { float a = x.x, b = x.y; red16x2(a, b); return (f32x2){a, b}; }
; DI void scan_bh2(const Args& a, int l, int bh, int halfsel, LAS unsigned char* lds) {
;     ...
;                 f32x2 sa = S[0] * kk4[0]; sa += S[1] * kk4[1]; f32x2 sb = S[2] * kk4[2]; sb += S[3] * kk4[3]; sa += sb;
;                 sa = red16p(sa); sa = -sa;
; #pragma unroll
;                 for (int j = 0; j < 4; ++j) S[j] = S[j] * d4[j] + sa * b4[j] + v2 * k4[j];
;                 f32x2 y = S[0] * r4[0]; y += S[1] * r4[1]; f32x2 yc = S[2] * r4[2]; yc += S[3] * r4[3]; y += yc;
;                 y = red16p(y);
;                 *(LAS unsigned*)(yb + st * 128 + row0 * 2) = pk2(y.x, y.y);
;                 if (st < T - 1) { r4 = nr4; d4 = nd4; k4 = nk4; kk4 = nkk4; b4 = nb4; v2 = nv2; }
	v_pk_mul_f32 v[60:61], v[28:29], v[2:3] op_sel:[0,0] op_sel_hi:[0,1]
	v_pk_mul_f32 v[64:65], v[24:25], v[36:37] op_sel:[0,0] op_sel_hi:[0,1]
	v_pk_fma_f32 v[60:61], v[28:29], v[4:5], v[60:61] op_sel:[1,0,0] op_sel_hi:[1,1,1]
	v_pk_mul_f32 v[14:15], v[24:25], v[36:37] op_sel:[1,0] op_sel_hi:[1,1]
	v_pk_fma_f32 v[60:61], v[30:31], v[6:7], v[60:61] op_sel:[0,0,0] op_sel_hi:[0,1,1]
	v_pk_fma_f32 v[2:3], v[20:21], v[2:3], v[64:65] op_sel:[0,0,0] op_sel_hi:[0,1,1]
	v_pk_fma_f32 v[60:61], v[30:31], v[8:9], v[60:61] op_sel:[1,0,0] op_sel_hi:[1,1,1]
	v_pk_fma_f32 v[4:5], v[20:21], v[4:5], v[14:15] op_sel:[1,0,0] op_sel_hi:[1,1,1]
	v_pk_mul_f32 v[64:65], v[26:27], v[36:37] op_sel:[0,0] op_sel_hi:[0,1]
	v_add_f32_dpp v60, v61, v60 quad_perm:[1,0,3,2] row_mask:0xf bank_mask:0xf bound_ctrl:1
	v_pk_mul_f32 v[14:15], v[26:27], v[36:37] op_sel:[1,0] op_sel_hi:[1,1]
	v_pk_fma_f32 v[6:7], v[22:23], v[6:7], v[64:65] op_sel:[0,0,0] op_sel_hi:[0,1,1]
	v_add_f32_dpp v60, v60, v60 quad_perm:[2,3,0,1] row_mask:0xf bank_mask:0xf bound_ctrl:1
	v_add_f32_dpp v62, v63, v62 quad_perm:[1,0,3,2] row_mask:0xf bank_mask:0xf bound_ctrl:1
	v_pk_fma_f32 v[8:9], v[22:23], v[8:9], v[14:15] op_sel:[1,0,0] op_sel_hi:[1,1,1]
	v_add_f32_dpp v60, v60, v60 row_half_mirror row_mask:0xf bank_mask:0xf bound_ctrl:1
	v_add_f32_dpp v62, v62, v62 quad_perm:[2,3,0,1] row_mask:0xf bank_mask:0xf bound_ctrl:1
	ds_read_b128 v[54:57], v250 offset:33280
	v_add_f32_dpp v60, v60, v60 row_mirror row_mask:0xf bank_mask:0xf bound_ctrl:1
	v_add_f32_dpp v62, v62, v62 row_half_mirror row_mask:0xf bank_mask:0xf bound_ctrl:1
	ds_read_b128 v[38:41], v250 offset:32256
	v_mov_b32_dpp v61, v60 quad_perm:[1,0,3,2] row_mask:0xf bank_mask:0xf bound_ctrl:1
	v_add_f32_dpp v62, v62, v62 row_mirror row_mask:0xf bank_mask:0xf bound_ctrl:1
	v_pk_fma_f32 v[2:3], v[32:33], v[60:61], v[2:3] op_sel:[0,0,0] op_sel_hi:[0,1,1] neg_lo:[0,1,0] neg_hi:[0,1,0]
	v_pk_fma_f32 v[4:5], v[32:33], v[60:61], v[4:5] op_sel:[1,0,0] op_sel_hi:[1,1,1] neg_lo:[0,1,0] neg_hi:[0,1,0]
	v_mov_b32_dpp v63, v62 quad_perm:[1,0,3,2] row_mask:0xf bank_mask:0xf bound_ctrl:1
	v_pk_fma_f32 v[6:7], v[34:35], v[60:61], v[6:7] op_sel:[0,0,0] op_sel_hi:[0,1,1] neg_lo:[0,1,0] neg_hi:[0,1,0]
	v_cvt_pk_bf16_f32 v64, v62, v63
	v_pk_fma_f32 v[8:9], v[34:35], v[60:61], v[8:9] op_sel:[1,0,0] op_sel_hi:[1,1,1] neg_lo:[0,1,0] neg_hi:[0,1,0]
	ds_write_b32 v253, v64 offset:2432
	v_pk_mul_f32 v[62:63], v[16:17], v[2:3] op_sel:[0,0] op_sel_hi:[0,1]
	ds_read_b128 v[28:31], v250 offset:34560
	v_pk_fma_f32 v[62:63], v[16:17], v[4:5], v[62:63] op_sel:[1,0,0] op_sel_hi:[1,1,1]
	ds_read_b32 v36, v251 offset:35072
	v_pk_fma_f32 v[62:63], v[18:19], v[6:7], v[62:63] op_sel:[0,0,0] op_sel_hi:[0,1,1]
	ds_read_b32 v37, v252 offset:35072
	v_pk_fma_f32 v[62:63], v[18:19], v[8:9], v[62:63] op_sel:[1,0,0] op_sel_hi:[1,1,1]
	ds_read_b128 v[24:27], v250 offset:34304
	ds_read_b128 v[20:23], v250 offset:34048
	s_waitcnt lgkmcnt(5)
	v_pk_mul_f32 v[60:61], v[50:51], v[2:3] op_sel:[0,0] op_sel_hi:[0,1]
	v_pk_mul_f32 v[64:65], v[46:47], v[58:59] op_sel:[0,0] op_sel_hi:[0,1]
	v_pk_fma_f32 v[60:61], v[50:51], v[4:5], v[60:61] op_sel:[1,0,0] op_sel_hi:[1,1,1]
	v_pk_mul_f32 v[14:15], v[46:47], v[58:59] op_sel:[1,0] op_sel_hi:[1,1]
	v_pk_fma_f32 v[60:61], v[52:53], v[6:7], v[60:61] op_sel:[0,0,0] op_sel_hi:[0,1,1]
	v_pk_fma_f32 v[2:3], v[42:43], v[2:3], v[64:65] op_sel:[0,0,0] op_sel_hi:[0,1,1]
	v_pk_fma_f32 v[60:61], v[52:53], v[8:9], v[60:61] op_sel:[1,0,0] op_sel_hi:[1,1,1]
	v_pk_fma_f32 v[4:5], v[42:43], v[4:5], v[14:15] op_sel:[1,0,0] op_sel_hi:[1,1,1]
	v_pk_mul_f32 v[64:65], v[48:49], v[58:59] op_sel:[0,0] op_sel_hi:[0,1]
	v_add_f32_dpp v60, v61, v60 quad_perm:[1,0,3,2] row_mask:0xf bank_mask:0xf bound_ctrl:1
	v_pk_mul_f32 v[14:15], v[48:49], v[58:59] op_sel:[1,0] op_sel_hi:[1,1]
	v_pk_fma_f32 v[6:7], v[44:45], v[6:7], v[64:65] op_sel:[0,0,0] op_sel_hi:[0,1,1]
	v_add_f32_dpp v60, v60, v60 quad_perm:[2,3,0,1] row_mask:0xf bank_mask:0xf bound_ctrl:1
	v_add_f32_dpp v62, v63, v62 quad_perm:[1,0,3,2] row_mask:0xf bank_mask:0xf bound_ctrl:1
	v_pk_fma_f32 v[8:9], v[44:45], v[8:9], v[14:15] op_sel:[1,0,0] op_sel_hi:[1,1,1]
	v_add_f32_dpp v60, v60, v60 row_half_mirror row_mask:0xf bank_mask:0xf bound_ctrl:1
	v_add_f32_dpp v62, v62, v62 quad_perm:[2,3,0,1] row_mask:0xf bank_mask:0xf bound_ctrl:1
	ds_read_b128 v[32:35], v250 offset:34816
	v_add_f32_dpp v60, v60, v60 row_mirror row_mask:0xf bank_mask:0xf bound_ctrl:1
	v_add_f32_dpp v62, v62, v62 row_half_mirror row_mask:0xf bank_mask:0xf bound_ctrl:1
	ds_read_b128 v[16:19], v250 offset:33792
	v_mov_b32_dpp v61, v60 quad_perm:[1,0,3,2] row_mask:0xf bank_mask:0xf bound_ctrl:1
	v_add_f32_dpp v62, v62, v62 row_mirror row_mask:0xf bank_mask:0xf bound_ctrl:1
	v_pk_fma_f32 v[2:3], v[54:55], v[60:61], v[2:3] op_sel:[0,0,0] op_sel_hi:[0,1,1] neg_lo:[0,1,0] neg_hi:[0,1,0]
	v_pk_fma_f32 v[4:5], v[54:55], v[60:61], v[4:5] op_sel:[1,0,0] op_sel_hi:[1,1,1] neg_lo:[0,1,0] neg_hi:[0,1,0]
	v_mov_b32_dpp v63, v62 quad_perm:[1,0,3,2] row_mask:0xf bank_mask:0xf bound_ctrl:1
	v_pk_fma_f32 v[6:7], v[56:57], v[60:61], v[6:7] op_sel:[0,0,0] op_sel_hi:[0,1,1] neg_lo:[0,1,0] neg_hi:[0,1,0]
	v_cvt_pk_bf16_f32 v64, v62, v63
	v_pk_fma_f32 v[8:9], v[56:57], v[60:61], v[8:9] op_sel:[1,0,0] op_sel_hi:[1,1,1] neg_lo:[0,1,0] neg_hi:[0,1,0]
	ds_write_b32 v253, v64 offset:2560
	v_pk_mul_f32 v[62:63], v[38:39], v[2:3] op_sel:[0,0] op_sel_hi:[0,1]
	ds_read_b128 v[50:53], v250 offset:36096
	v_pk_fma_f32 v[62:63], v[38:39], v[4:5], v[62:63] op_sel:[1,0,0] op_sel_hi:[1,1,1]
	ds_read_b32 v58, v251 offset:36608
	v_pk_fma_f32 v[62:63], v[40:41], v[6:7], v[62:63] op_sel:[0,0,0] op_sel_hi:[0,1,1]
	ds_read_b32 v59, v252 offset:36608
	v_pk_fma_f32 v[62:63], v[40:41], v[8:9], v[62:63] op_sel:[1,0,0] op_sel_hi:[1,1,1]
	ds_read_b128 v[46:49], v250 offset:35840
	ds_read_b128 v[42:45], v250 offset:35584
	s_waitcnt lgkmcnt(5)
; #define LAS __attribute__((address_space(3)))
; DI unsigned pk2(float a, float b) { f32x2 v = {a, b}; bf2_t r = __builtin_convertvector(v, bf2_t); return __builtin_bit_cast(unsigned, r); }
; DI f32x2 red16p(f32x2 x) { float a = x.x, b = x.y; red16x2(a, b); return (f32x2){a, b}; }
; DI void scan_bh2(const Args& a, int l, int bh, int halfsel, LAS unsigned char* lds) {
;     ...
;                 f32x2 sa = S[0] * kk4[0]; sa += S[1] * kk4[1]; f32x2 sb = S[2] * kk4[2]; sb += S[3] * kk4[3]; sa += sb;
;                 sa = red16p(sa); sa = -sa;
; #pragma unroll
;                 for (int j = 0; j < 4; ++j) S[j] = S[j] * d4[j] + sa * b4[j] + v2 * k4[j];
;                 f32x2 y = S[0] * r4[0]; y += S[1] * r4[1]; f32x2 yc = S[2] * r4[2]; yc += S[3] * r4[3]; y += yc;
;                 y = red16p(y);
;                 *(LAS unsigned*)(yb + st * 128 + row0 * 2) = pk2(y.x, y.y);
;                 if (st < T - 1) { r4 = nr4; d4 = nd4; k4 = nk4; kk4 = nkk4; b4 = nb4; v2 = nv2; }
	v_pk_mul_f32 v[60:61], v[28:29], v[2:3] op_sel:[0,0] op_sel_hi:[0,1]
	v_pk_mul_f32 v[64:65], v[24:25], v[36:37] op_sel:[0,0] op_sel_hi:[0,1]
	v_pk_fma_f32 v[60:61], v[28:29], v[4:5], v[60:61] op_sel:[1,0,0] op_sel_hi:[1,1,1]
	v_pk_mul_f32 v[14:15], v[24:25], v[36:37] op_sel:[1,0] op_sel_hi:[1,1]
	v_pk_fma_f32 v[60:61], v[30:31], v[6:7], v[60:61] op_sel:[0,0,0] op_sel_hi:[0,1,1]
	v_pk_fma_f32 v[2:3], v[20:21], v[2:3], v[64:65] op_sel:[0,0,0] op_sel_hi:[0,1,1]
	v_pk_fma_f32 v[60:61], v[30:31], v[8:9], v[60:61] op_sel:[1,0,0] op_sel_hi:[1,1,1]
	v_pk_fma_f32 v[4:5], v[20:21], v[4:5], v[14:15] op_sel:[1,0,0] op_sel_hi:[1,1,1]
	v_pk_mul_f32 v[64:65], v[26:27], v[36:37] op_sel:[0,0] op_sel_hi:[0,1]
	v_add_f32_dpp v60, v61, v60 quad_perm:[1,0,3,2] row_mask:0xf bank_mask:0xf bound_ctrl:1
	v_pk_mul_f32 v[14:15], v[26:27], v[36:37] op_sel:[1,0] op_sel_hi:[1,1]
	v_pk_fma_f32 v[6:7], v[22:23], v[6:7], v[64:65] op_sel:[0,0,0] op_sel_hi:[0,1,1]
	v_add_f32_dpp v60, v60, v60 quad_perm:[2,3,0,1] row_mask:0xf bank_mask:0xf bound_ctrl:1
	v_add_f32_dpp v62, v63, v62 quad_perm:[1,0,3,2] row_mask:0xf bank_mask:0xf bound_ctrl:1
	v_pk_fma_f32 v[8:9], v[22:23], v[8:9], v[14:15] op_sel:[1,0,0] op_sel_hi:[1,1,1]
	v_add_f32_dpp v60, v60, v60 row_half_mirror row_mask:0xf bank_mask:0xf bound_ctrl:1
	v_add_f32_dpp v62, v62, v62 quad_perm:[2,3,0,1] row_mask:0xf bank_mask:0xf bound_ctrl:1
	ds_read_b128 v[54:57], v250 offset:36352
	v_add_f32_dpp v60, v60, v60 row_mirror row_mask:0xf bank_mask:0xf bound_ctrl:1
	v_add_f32_dpp v62, v62, v62 row_half_mirror row_mask:0xf bank_mask:0xf bound_ctrl:1
	ds_read_b128 v[38:41], v250 offset:35328
	v_mov_b32_dpp v61, v60 quad_perm:[1,0,3,2] row_mask:0xf bank_mask:0xf bound_ctrl:1
	v_add_f32_dpp v62, v62, v62 row_mirror row_mask:0xf bank_mask:0xf bound_ctrl:1
	v_pk_fma_f32 v[2:3], v[32:33], v[60:61], v[2:3] op_sel:[0,0,0] op_sel_hi:[0,1,1] neg_lo:[0,1,0] neg_hi:[0,1,0]
	v_pk_fma_f32 v[4:5], v[32:33], v[60:61], v[4:5] op_sel:[1,0,0] op_sel_hi:[1,1,1] neg_lo:[0,1,0] neg_hi:[0,1,0]
	v_mov_b32_dpp v63, v62 quad_perm:[1,0,3,2] row_mask:0xf bank_mask:0xf bound_ctrl:1
	v_pk_fma_f32 v[6:7], v[34:35], v[60:61], v[6:7] op_sel:[0,0,0] op_sel_hi:[0,1,1] neg_lo:[0,1,0] neg_hi:[0,1,0]
	v_cvt_pk_bf16_f32 v64, v62, v63
	v_pk_fma_f32 v[8:9], v[34:35], v[60:61], v[8:9] op_sel:[1,0,0] op_sel_hi:[1,1,1] neg_lo:[0,1,0] neg_hi:[0,1,0]
	ds_write_b32 v253, v64 offset:2688
	v_pk_mul_f32 v[62:63], v[16:17], v[2:3] op_sel:[0,0] op_sel_hi:[0,1]
	ds_read_b128 v[28:31], v250 offset:37632
	v_pk_fma_f32 v[62:63], v[16:17], v[4:5], v[62:63] op_sel:[1,0,0] op_sel_hi:[1,1,1]
	ds_read_b32 v36, v251 offset:38144
	v_pk_fma_f32 v[62:63], v[18:19], v[6:7], v[62:63] op_sel:[0,0,0] op_sel_hi:[0,1,1]
	ds_read_b32 v37, v252 offset:38144
	v_pk_fma_f32 v[62:63], v[18:19], v[8:9], v[62:63] op_sel:[1,0,0] op_sel_hi:[1,1,1]
	ds_read_b128 v[24:27], v250 offset:37376
	ds_read_b128 v[20:23], v250 offset:37120
	s_waitcnt lgkmcnt(5)
	v_pk_mul_f32 v[60:61], v[50:51], v[2:3] op_sel:[0,0] op_sel_hi:[0,1]
	v_pk_mul_f32 v[64:65], v[46:47], v[58:59] op_sel:[0,0] op_sel_hi:[0,1]
	v_pk_fma_f32 v[60:61], v[50:51], v[4:5], v[60:61] op_sel:[1,0,0] op_sel_hi:[1,1,1]
	v_pk_mul_f32 v[14:15], v[46:47], v[58:59] op_sel:[1,0] op_sel_hi:[1,1]
	v_pk_fma_f32 v[60:61], v[52:53], v[6:7], v[60:61] op_sel:[0,0,0] op_sel_hi:[0,1,1]
	v_pk_fma_f32 v[2:3], v[42:43], v[2:3], v[64:65] op_sel:[0,0,0] op_sel_hi:[0,1,1]
	v_pk_fma_f32 v[60:61], v[52:53], v[8:9], v[60:61] op_sel:[1,0,0] op_sel_hi:[1,1,1]
	v_pk_fma_f32 v[4:5], v[42:43], v[4:5], v[14:15] op_sel:[1,0,0] op_sel_hi:[1,1,1]
	v_pk_mul_f32 v[64:65], v[48:49], v[58:59] op_sel:[0,0] op_sel_hi:[0,1]
	v_add_f32_dpp v60, v61, v60 quad_perm:[1,0,3,2] row_mask:0xf bank_mask:0xf bound_ctrl:1
	v_pk_mul_f32 v[14:15], v[48:49], v[58:59] op_sel:[1,0] op_sel_hi:[1,1]
	v_pk_fma_f32 v[6:7], v[44:45], v[6:7], v[64:65] op_sel:[0,0,0] op_sel_hi:[0,1,1]
	v_add_f32_dpp v60, v60, v60 quad_perm:[2,3,0,1] row_mask:0xf bank_mask:0xf bound_ctrl:1
	v_add_f32_dpp v62, v63, v62 quad_perm:[1,0,3,2] row_mask:0xf bank_mask:0xf bound_ctrl:1
	v_pk_fma_f32 v[8:9], v[44:45], v[8:9], v[14:15] op_sel:[1,0,0] op_sel_hi:[1,1,1]
	v_add_f32_dpp v60, v60, v60 row_half_mirror row_mask:0xf bank_mask:0xf bound_ctrl:1
	v_add_f32_dpp v62, v62, v62 quad_perm:[2,3,0,1] row_mask:0xf bank_mask:0xf bound_ctrl:1
	ds_read_b128 v[32:35], v250 offset:37888
	v_add_f32_dpp v60, v60, v60 row_mirror row_mask:0xf bank_mask:0xf bound_ctrl:1
	v_add_f32_dpp v62, v62, v62 row_half_mirror row_mask:0xf bank_mask:0xf bound_ctrl:1
	ds_read_b128 v[16:19], v250 offset:36864
	v_mov_b32_dpp v61, v60 quad_perm:[1,0,3,2] row_mask:0xf bank_mask:0xf bound_ctrl:1
	v_add_f32_dpp v62, v62, v62 row_mirror row_mask:0xf bank_mask:0xf bound_ctrl:1
	v_pk_fma_f32 v[2:3], v[54:55], v[60:61], v[2:3] op_sel:[0,0,0] op_sel_hi:[0,1,1] neg_lo:[0,1,0] neg_hi:[0,1,0]
	v_pk_fma_f32 v[4:5], v[54:55], v[60:61], v[4:5] op_sel:[1,0,0] op_sel_hi:[1,1,1] neg_lo:[0,1,0] neg_hi:[0,1,0]
	v_mov_b32_dpp v63, v62 quad_perm:[1,0,3,2] row_mask:0xf bank_mask:0xf bound_ctrl:1
	v_pk_fma_f32 v[6:7], v[56:57], v[60:61], v[6:7] op_sel:[0,0,0] op_sel_hi:[0,1,1] neg_lo:[0,1,0] neg_hi:[0,1,0]
	v_cvt_pk_bf16_f32 v64, v62, v63
	v_pk_fma_f32 v[8:9], v[56:57], v[60:61], v[8:9] op_sel:[1,0,0] op_sel_hi:[1,1,1] neg_lo:[0,1,0] neg_hi:[0,1,0]
	ds_write_b32 v253, v64 offset:2816
	v_pk_mul_f32 v[62:63], v[38:39], v[2:3] op_sel:[0,0] op_sel_hi:[0,1]
	ds_read_b128 v[50:53], v250 offset:39168
	v_pk_fma_f32 v[62:63], v[38:39], v[4:5], v[62:63] op_sel:[1,0,0] op_sel_hi:[1,1,1]
	ds_read_b32 v58, v251 offset:39680
	v_pk_fma_f32 v[62:63], v[40:41], v[6:7], v[62:63] op_sel:[0,0,0] op_sel_hi:[0,1,1]
	ds_read_b32 v59, v252 offset:39680
	v_pk_fma_f32 v[62:63], v[40:41], v[8:9], v[62:63] op_sel:[1,0,0] op_sel_hi:[1,1,1]
	ds_read_b128 v[46:49], v250 offset:38912
	ds_read_b128 v[42:45], v250 offset:38656
	s_waitcnt lgkmcnt(5)
; #define LAS __attribute__((address_space(3)))
; DI unsigned pk2(float a, float b) { f32x2 v = {a, b}; bf2_t r = __builtin_convertvector(v, bf2_t); return __builtin_bit_cast(unsigned, r); }
; DI f32x2 red16p(f32x2 x) { float a = x.x, b = x.y; red16x2(a, b); return (f32x2){a, b}; }
; DI void scan_bh2(const Args& a, int l, int bh, int halfsel, LAS unsigned char* lds) {
;     ...
;                 f32x2 sa = S[0] * kk4[0]; sa += S[1] * kk4[1]; f32x2 sb = S[2] * kk4[2]; sb += S[3] * kk4[3]; sa += sb;
;                 sa = red16p(sa); sa = -sa;
; #pragma unroll
;                 for (int j = 0; j < 4; ++j) S[j] = S[j] * d4[j] + sa * b4[j] + v2 * k4[j];
;                 f32x2 y = S[0] * r4[0]; y += S[1] * r4[1]; f32x2 yc = S[2] * r4[2]; yc += S[3] * r4[3]; y += yc;
;                 y = red16p(y);
;                 *(LAS unsigned*)(yb + st * 128 + row0 * 2) = pk2(y.x, y.y);
;                 if (st < T - 1) { r4 = nr4; d4 = nd4; k4 = nk4; kk4 = nkk4; b4 = nb4; v2 = nv2; }
	v_pk_mul_f32 v[60:61], v[28:29], v[2:3] op_sel:[0,0] op_sel_hi:[0,1]
	v_pk_mul_f32 v[64:65], v[24:25], v[36:37] op_sel:[0,0] op_sel_hi:[0,1]
	v_pk_fma_f32 v[60:61], v[28:29], v[4:5], v[60:61] op_sel:[1,0,0] op_sel_hi:[1,1,1]
	v_pk_mul_f32 v[14:15], v[24:25], v[36:37] op_sel:[1,0] op_sel_hi:[1,1]
	v_pk_fma_f32 v[60:61], v[30:31], v[6:7], v[60:61] op_sel:[0,0,0] op_sel_hi:[0,1,1]
	v_pk_fma_f32 v[2:3], v[20:21], v[2:3], v[64:65] op_sel:[0,0,0] op_sel_hi:[0,1,1]
	v_pk_fma_f32 v[60:61], v[30:31], v[8:9], v[60:61] op_sel:[1,0,0] op_sel_hi:[1,1,1]
	v_pk_fma_f32 v[4:5], v[20:21], v[4:5], v[14:15] op_sel:[1,0,0] op_sel_hi:[1,1,1]
	v_pk_mul_f32 v[64:65], v[26:27], v[36:37] op_sel:[0,0] op_sel_hi:[0,1]
	v_add_f32_dpp v60, v61, v60 quad_perm:[1,0,3,2] row_mask:0xf bank_mask:0xf bound_ctrl:1
	v_pk_mul_f32 v[14:15], v[26:27], v[36:37] op_sel:[1,0] op_sel_hi:[1,1]
	v_pk_fma_f32 v[6:7], v[22:23], v[6:7], v[64:65] op_sel:[0,0,0] op_sel_hi:[0,1,1]
	v_add_f32_dpp v60, v60, v60 quad_perm:[2,3,0,1] row_mask:0xf bank_mask:0xf bound_ctrl:1
	v_add_f32_dpp v62, v63, v62 quad_perm:[1,0,3,2] row_mask:0xf bank_mask:0xf bound_ctrl:1
	v_pk_fma_f32 v[8:9], v[22:23], v[8:9], v[14:15] op_sel:[1,0,0] op_sel_hi:[1,1,1]
	v_add_f32_dpp v60, v60, v60 row_half_mirror row_mask:0xf bank_mask:0xf bound_ctrl:1
	v_add_f32_dpp v62, v62, v62 quad_perm:[2,3,0,1] row_mask:0xf bank_mask:0xf bound_ctrl:1
	ds_read_b128 v[54:57], v250 offset:39424
	v_add_f32_dpp v60, v60, v60 row_mirror row_mask:0xf bank_mask:0xf bound_ctrl:1
	v_add_f32_dpp v62, v62, v62 row_half_mirror row_mask:0xf bank_mask:0xf bound_ctrl:1
	ds_read_b128 v[38:41], v250 offset:38400
	v_mov_b32_dpp v61, v60 quad_perm:[1,0,3,2] row_mask:0xf bank_mask:0xf bound_ctrl:1
	v_add_f32_dpp v62, v62, v62 row_mirror row_mask:0xf bank_mask:0xf bound_ctrl:1
	v_pk_fma_f32 v[2:3], v[32:33], v[60:61], v[2:3] op_sel:[0,0,0] op_sel_hi:[0,1,1] neg_lo:[0,1,0] neg_hi:[0,1,0]
	v_pk_fma_f32 v[4:5], v[32:33], v[60:61], v[4:5] op_sel:[1,0,0] op_sel_hi:[1,1,1] neg_lo:[0,1,0] neg_hi:[0,1,0]
	v_mov_b32_dpp v63, v62 quad_perm:[1,0,3,2] row_mask:0xf bank_mask:0xf bound_ctrl:1
	v_pk_fma_f32 v[6:7], v[34:35], v[60:61], v[6:7] op_sel:[0,0,0] op_sel_hi:[0,1,1] neg_lo:[0,1,0] neg_hi:[0,1,0]
	v_cvt_pk_bf16_f32 v64, v62, v63
	v_pk_fma_f32 v[8:9], v[34:35], v[60:61], v[8:9] op_sel:[1,0,0] op_sel_hi:[1,1,1] neg_lo:[0,1,0] neg_hi:[0,1,0]
	ds_write_b32 v253, v64 offset:2944
	v_pk_mul_f32 v[62:63], v[16:17], v[2:3] op_sel:[0,0] op_sel_hi:[0,1]
	ds_read_b128 v[28:31], v250 offset:40704
	v_pk_fma_f32 v[62:63], v[16:17], v[4:5], v[62:63] op_sel:[1,0,0] op_sel_hi:[1,1,1]
	ds_read_b32 v36, v251 offset:41216
	v_pk_fma_f32 v[62:63], v[18:19], v[6:7], v[62:63] op_sel:[0,0,0] op_sel_hi:[0,1,1]
	ds_read_b32 v37, v252 offset:41216
	v_pk_fma_f32 v[62:63], v[18:19], v[8:9], v[62:63] op_sel:[1,0,0] op_sel_hi:[1,1,1]
	ds_read_b128 v[24:27], v250 offset:40448
	ds_read_b128 v[20:23], v250 offset:40192
	s_waitcnt lgkmcnt(5)
	v_pk_mul_f32 v[60:61], v[50:51], v[2:3] op_sel:[0,0] op_sel_hi:[0,1]
	v_pk_mul_f32 v[64:65], v[46:47], v[58:59] op_sel:[0,0] op_sel_hi:[0,1]
	v_pk_fma_f32 v[60:61], v[50:51], v[4:5], v[60:61] op_sel:[1,0,0] op_sel_hi:[1,1,1]
	v_pk_mul_f32 v[14:15], v[46:47], v[58:59] op_sel:[1,0] op_sel_hi:[1,1]
	v_pk_fma_f32 v[60:61], v[52:53], v[6:7], v[60:61] op_sel:[0,0,0] op_sel_hi:[0,1,1]
	v_pk_fma_f32 v[2:3], v[42:43], v[2:3], v[64:65] op_sel:[0,0,0] op_sel_hi:[0,1,1]
	v_pk_fma_f32 v[60:61], v[52:53], v[8:9], v[60:61] op_sel:[1,0,0] op_sel_hi:[1,1,1]
	v_pk_fma_f32 v[4:5], v[42:43], v[4:5], v[14:15] op_sel:[1,0,0] op_sel_hi:[1,1,1]
	v_pk_mul_f32 v[64:65], v[48:49], v[58:59] op_sel:[0,0] op_sel_hi:[0,1]
	v_add_f32_dpp v60, v61, v60 quad_perm:[1,0,3,2] row_mask:0xf bank_mask:0xf bound_ctrl:1
	v_pk_mul_f32 v[14:15], v[48:49], v[58:59] op_sel:[1,0] op_sel_hi:[1,1]
	v_pk_fma_f32 v[6:7], v[44:45], v[6:7], v[64:65] op_sel:[0,0,0] op_sel_hi:[0,1,1]
	v_add_f32_dpp v60, v60, v60 quad_perm:[2,3,0,1] row_mask:0xf bank_mask:0xf bound_ctrl:1
	v_add_f32_dpp v62, v63, v62 quad_perm:[1,0,3,2] row_mask:0xf bank_mask:0xf bound_ctrl:1
	v_pk_fma_f32 v[8:9], v[44:45], v[8:9], v[14:15] op_sel:[1,0,0] op_sel_hi:[1,1,1]
	v_add_f32_dpp v60, v60, v60 row_half_mirror row_mask:0xf bank_mask:0xf bound_ctrl:1
	v_add_f32_dpp v62, v62, v62 quad_perm:[2,3,0,1] row_mask:0xf bank_mask:0xf bound_ctrl:1
	ds_read_b128 v[32:35], v250 offset:40960
	v_add_f32_dpp v60, v60, v60 row_mirror row_mask:0xf bank_mask:0xf bound_ctrl:1
	v_add_f32_dpp v62, v62, v62 row_half_mirror row_mask:0xf bank_mask:0xf bound_ctrl:1
	ds_read_b128 v[16:19], v250 offset:39936
	v_mov_b32_dpp v61, v60 quad_perm:[1,0,3,2] row_mask:0xf bank_mask:0xf bound_ctrl:1
	v_add_f32_dpp v62, v62, v62 row_mirror row_mask:0xf bank_mask:0xf bound_ctrl:1
	v_pk_fma_f32 v[2:3], v[54:55], v[60:61], v[2:3] op_sel:[0,0,0] op_sel_hi:[0,1,1] neg_lo:[0,1,0] neg_hi:[0,1,0]
	v_pk_fma_f32 v[4:5], v[54:55], v[60:61], v[4:5] op_sel:[1,0,0] op_sel_hi:[1,1,1] neg_lo:[0,1,0] neg_hi:[0,1,0]
	v_mov_b32_dpp v63, v62 quad_perm:[1,0,3,2] row_mask:0xf bank_mask:0xf bound_ctrl:1
	v_pk_fma_f32 v[6:7], v[56:57], v[60:61], v[6:7] op_sel:[0,0,0] op_sel_hi:[0,1,1] neg_lo:[0,1,0] neg_hi:[0,1,0]
	v_cvt_pk_bf16_f32 v64, v62, v63
	v_pk_fma_f32 v[8:9], v[56:57], v[60:61], v[8:9] op_sel:[1,0,0] op_sel_hi:[1,1,1] neg_lo:[0,1,0] neg_hi:[0,1,0]
	ds_write_b32 v253, v64 offset:3072
	v_pk_mul_f32 v[62:63], v[38:39], v[2:3] op_sel:[0,0] op_sel_hi:[0,1]
	ds_read_b128 v[50:53], v250 offset:42240
	v_pk_fma_f32 v[62:63], v[38:39], v[4:5], v[62:63] op_sel:[1,0,0] op_sel_hi:[1,1,1]
	ds_read_b32 v58, v251 offset:42752
	v_pk_fma_f32 v[62:63], v[40:41], v[6:7], v[62:63] op_sel:[0,0,0] op_sel_hi:[0,1,1]
	ds_read_b32 v59, v252 offset:42752
	v_pk_fma_f32 v[62:63], v[40:41], v[8:9], v[62:63] op_sel:[1,0,0] op_sel_hi:[1,1,1]
	ds_read_b128 v[46:49], v250 offset:41984
	ds_read_b128 v[42:45], v250 offset:41728
	s_waitcnt lgkmcnt(5)
; #define LAS __attribute__((address_space(3)))
; DI unsigned pk2(float a, float b) { f32x2 v = {a, b}; bf2_t r = __builtin_convertvector(v, bf2_t); return __builtin_bit_cast(unsigned, r); }
; DI f32x2 red16p(f32x2 x) { float a = x.x, b = x.y; red16x2(a, b); return (f32x2){a, b}; }
; DI void scan_bh2(const Args& a, int l, int bh, int halfsel, LAS unsigned char* lds) {
;     ...
;                 f32x2 sa = S[0] * kk4[0]; sa += S[1] * kk4[1]; f32x2 sb = S[2] * kk4[2]; sb += S[3] * kk4[3]; sa += sb;
;                 sa = red16p(sa); sa = -sa;
; #pragma unroll
;                 for (int j = 0; j < 4; ++j) S[j] = S[j] * d4[j] + sa * b4[j] + v2 * k4[j];
;                 f32x2 y = S[0] * r4[0]; y += S[1] * r4[1]; f32x2 yc = S[2] * r4[2]; yc += S[3] * r4[3]; y += yc;
;                 y = red16p(y);
;                 *(LAS unsigned*)(yb + st * 128 + row0 * 2) = pk2(y.x, y.y);
;                 if (st < T - 1) { r4 = nr4; d4 = nd4; k4 = nk4; kk4 = nkk4; b4 = nb4; v2 = nv2; }
	v_pk_mul_f32 v[60:61], v[28:29], v[2:3] op_sel:[0,0] op_sel_hi:[0,1]
	v_pk_mul_f32 v[64:65], v[24:25], v[36:37] op_sel:[0,0] op_sel_hi:[0,1]
	v_pk_fma_f32 v[60:61], v[28:29], v[4:5], v[60:61] op_sel:[1,0,0] op_sel_hi:[1,1,1]
	v_pk_mul_f32 v[14:15], v[24:25], v[36:37] op_sel:[1,0] op_sel_hi:[1,1]
	v_pk_fma_f32 v[60:61], v[30:31], v[6:7], v[60:61] op_sel:[0,0,0] op_sel_hi:[0,1,1]
	v_pk_fma_f32 v[2:3], v[20:21], v[2:3], v[64:65] op_sel:[0,0,0] op_sel_hi:[0,1,1]
	v_pk_fma_f32 v[60:61], v[30:31], v[8:9], v[60:61] op_sel:[1,0,0] op_sel_hi:[1,1,1]
	v_pk_fma_f32 v[4:5], v[20:21], v[4:5], v[14:15] op_sel:[1,0,0] op_sel_hi:[1,1,1]
	v_pk_mul_f32 v[64:65], v[26:27], v[36:37] op_sel:[0,0] op_sel_hi:[0,1]
	v_add_f32_dpp v60, v61, v60 quad_perm:[1,0,3,2] row_mask:0xf bank_mask:0xf bound_ctrl:1
	v_pk_mul_f32 v[14:15], v[26:27], v[36:37] op_sel:[1,0] op_sel_hi:[1,1]
	v_pk_fma_f32 v[6:7], v[22:23], v[6:7], v[64:65] op_sel:[0,0,0] op_sel_hi:[0,1,1]
	v_add_f32_dpp v60, v60, v60 quad_perm:[2,3,0,1] row_mask:0xf bank_mask:0xf bound_ctrl:1
	v_add_f32_dpp v62, v63, v62 quad_perm:[1,0,3,2] row_mask:0xf bank_mask:0xf bound_ctrl:1
	v_pk_fma_f32 v[8:9], v[22:23], v[8:9], v[14:15] op_sel:[1,0,0] op_sel_hi:[1,1,1]
	v_add_f32_dpp v60, v60, v60 row_half_mirror row_mask:0xf bank_mask:0xf bound_ctrl:1
	v_add_f32_dpp v62, v62, v62 quad_perm:[2,3,0,1] row_mask:0xf bank_mask:0xf bound_ctrl:1
	ds_read_b128 v[54:57], v250 offset:42496
	v_add_f32_dpp v60, v60, v60 row_mirror row_mask:0xf bank_mask:0xf bound_ctrl:1
	v_add_f32_dpp v62, v62, v62 row_half_mirror row_mask:0xf bank_mask:0xf bound_ctrl:1
	ds_read_b128 v[38:41], v250 offset:41472
	v_mov_b32_dpp v61, v60 quad_perm:[1,0,3,2] row_mask:0xf bank_mask:0xf bound_ctrl:1
	v_add_f32_dpp v62, v62, v62 row_mirror row_mask:0xf bank_mask:0xf bound_ctrl:1
	v_pk_fma_f32 v[2:3], v[32:33], v[60:61], v[2:3] op_sel:[0,0,0] op_sel_hi:[0,1,1] neg_lo:[0,1,0] neg_hi:[0,1,0]
	v_pk_fma_f32 v[4:5], v[32:33], v[60:61], v[4:5] op_sel:[1,0,0] op_sel_hi:[1,1,1] neg_lo:[0,1,0] neg_hi:[0,1,0]
	v_mov_b32_dpp v63, v62 quad_perm:[1,0,3,2] row_mask:0xf bank_mask:0xf bound_ctrl:1
	v_pk_fma_f32 v[6:7], v[34:35], v[60:61], v[6:7] op_sel:[0,0,0] op_sel_hi:[0,1,1] neg_lo:[0,1,0] neg_hi:[0,1,0]
	v_cvt_pk_bf16_f32 v64, v62, v63
	v_pk_fma_f32 v[8:9], v[34:35], v[60:61], v[8:9] op_sel:[1,0,0] op_sel_hi:[1,1,1] neg_lo:[0,1,0] neg_hi:[0,1,0]
	ds_write_b32 v253, v64 offset:3200
	v_pk_mul_f32 v[62:63], v[16:17], v[2:3] op_sel:[0,0] op_sel_hi:[0,1]
	ds_read_b128 v[28:31], v250 offset:43776
	v_pk_fma_f32 v[62:63], v[16:17], v[4:5], v[62:63] op_sel:[1,0,0] op_sel_hi:[1,1,1]
	ds_read_b32 v36, v251 offset:44288
	v_pk_fma_f32 v[62:63], v[18:19], v[6:7], v[62:63] op_sel:[0,0,0] op_sel_hi:[0,1,1]
	ds_read_b32 v37, v252 offset:44288
	v_pk_fma_f32 v[62:63], v[18:19], v[8:9], v[62:63] op_sel:[1,0,0] op_sel_hi:[1,1,1]
	ds_read_b128 v[24:27], v250 offset:43520
	ds_read_b128 v[20:23], v250 offset:43264
	s_waitcnt lgkmcnt(5)
	v_pk_mul_f32 v[60:61], v[50:51], v[2:3] op_sel:[0,0] op_sel_hi:[0,1]
	v_pk_mul_f32 v[64:65], v[46:47], v[58:59] op_sel:[0,0] op_sel_hi:[0,1]
	v_pk_fma_f32 v[60:61], v[50:51], v[4:5], v[60:61] op_sel:[1,0,0] op_sel_hi:[1,1,1]
	v_pk_mul_f32 v[14:15], v[46:47], v[58:59] op_sel:[1,0] op_sel_hi:[1,1]
	v_pk_fma_f32 v[60:61], v[52:53], v[6:7], v[60:61] op_sel:[0,0,0] op_sel_hi:[0,1,1]
	v_pk_fma_f32 v[2:3], v[42:43], v[2:3], v[64:65] op_sel:[0,0,0] op_sel_hi:[0,1,1]
	v_pk_fma_f32 v[60:61], v[52:53], v[8:9], v[60:61] op_sel:[1,0,0] op_sel_hi:[1,1,1]
	v_pk_fma_f32 v[4:5], v[42:43], v[4:5], v[14:15] op_sel:[1,0,0] op_sel_hi:[1,1,1]
	v_pk_mul_f32 v[64:65], v[48:49], v[58:59] op_sel:[0,0] op_sel_hi:[0,1]
	v_add_f32_dpp v60, v61, v60 quad_perm:[1,0,3,2] row_mask:0xf bank_mask:0xf bound_ctrl:1
	v_pk_mul_f32 v[14:15], v[48:49], v[58:59] op_sel:[1,0] op_sel_hi:[1,1]
	v_pk_fma_f32 v[6:7], v[44:45], v[6:7], v[64:65] op_sel:[0,0,0] op_sel_hi:[0,1,1]
	v_add_f32_dpp v60, v60, v60 quad_perm:[2,3,0,1] row_mask:0xf bank_mask:0xf bound_ctrl:1
	v_add_f32_dpp v62, v63, v62 quad_perm:[1,0,3,2] row_mask:0xf bank_mask:0xf bound_ctrl:1
	v_pk_fma_f32 v[8:9], v[44:45], v[8:9], v[14:15] op_sel:[1,0,0] op_sel_hi:[1,1,1]
	v_add_f32_dpp v60, v60, v60 row_half_mirror row_mask:0xf bank_mask:0xf bound_ctrl:1
	v_add_f32_dpp v62, v62, v62 quad_perm:[2,3,0,1] row_mask:0xf bank_mask:0xf bound_ctrl:1
	ds_read_b128 v[32:35], v250 offset:44032
	v_add_f32_dpp v60, v60, v60 row_mirror row_mask:0xf bank_mask:0xf bound_ctrl:1
	v_add_f32_dpp v62, v62, v62 row_half_mirror row_mask:0xf bank_mask:0xf bound_ctrl:1
	ds_read_b128 v[16:19], v250 offset:43008
	v_mov_b32_dpp v61, v60 quad_perm:[1,0,3,2] row_mask:0xf bank_mask:0xf bound_ctrl:1
	v_add_f32_dpp v62, v62, v62 row_mirror row_mask:0xf bank_mask:0xf bound_ctrl:1
	v_pk_fma_f32 v[2:3], v[54:55], v[60:61], v[2:3] op_sel:[0,0,0] op_sel_hi:[0,1,1] neg_lo:[0,1,0] neg_hi:[0,1,0]
	v_pk_fma_f32 v[4:5], v[54:55], v[60:61], v[4:5] op_sel:[1,0,0] op_sel_hi:[1,1,1] neg_lo:[0,1,0] neg_hi:[0,1,0]
	v_mov_b32_dpp v63, v62 quad_perm:[1,0,3,2] row_mask:0xf bank_mask:0xf bound_ctrl:1
	v_pk_fma_f32 v[6:7], v[56:57], v[60:61], v[6:7] op_sel:[0,0,0] op_sel_hi:[0,1,1] neg_lo:[0,1,0] neg_hi:[0,1,0]
	v_cvt_pk_bf16_f32 v64, v62, v63
	v_pk_fma_f32 v[8:9], v[56:57], v[60:61], v[8:9] op_sel:[1,0,0] op_sel_hi:[1,1,1] neg_lo:[0,1,0] neg_hi:[0,1,0]
	ds_write_b32 v253, v64 offset:3328
	v_pk_mul_f32 v[62:63], v[38:39], v[2:3] op_sel:[0,0] op_sel_hi:[0,1]
	ds_read_b128 v[50:53], v250 offset:45312
	v_pk_fma_f32 v[62:63], v[38:39], v[4:5], v[62:63] op_sel:[1,0,0] op_sel_hi:[1,1,1]
	ds_read_b32 v58, v251 offset:45824
	v_pk_fma_f32 v[62:63], v[40:41], v[6:7], v[62:63] op_sel:[0,0,0] op_sel_hi:[0,1,1]
	ds_read_b32 v59, v252 offset:45824
	v_pk_fma_f32 v[62:63], v[40:41], v[8:9], v[62:63] op_sel:[1,0,0] op_sel_hi:[1,1,1]
	ds_read_b128 v[46:49], v250 offset:45056
	ds_read_b128 v[42:45], v250 offset:44800
	s_waitcnt lgkmcnt(5)
; #define LAS __attribute__((address_space(3)))
; DI unsigned pk2(float a, float b) { f32x2 v = {a, b}; bf2_t r = __builtin_convertvector(v, bf2_t); return __builtin_bit_cast(unsigned, r); }
; DI f32x2 red16p(f32x2 x) { float a = x.x, b = x.y; red16x2(a, b); return (f32x2){a, b}; }
; DI void scan_bh2(const Args& a, int l, int bh, int halfsel, LAS unsigned char* lds) {
;     ...
;                 f32x2 sa = S[0] * kk4[0]; sa += S[1] * kk4[1]; f32x2 sb = S[2] * kk4[2]; sb += S[3] * kk4[3]; sa += sb;
;                 sa = red16p(sa); sa = -sa;
; #pragma unroll
;                 for (int j = 0; j < 4; ++j) S[j] = S[j] * d4[j] + sa * b4[j] + v2 * k4[j];
;                 f32x2 y = S[0] * r4[0]; y += S[1] * r4[1]; f32x2 yc = S[2] * r4[2]; yc += S[3] * r4[3]; y += yc;
;                 y = red16p(y);
;                 *(LAS unsigned*)(yb + st * 128 + row0 * 2) = pk2(y.x, y.y);
;                 if (st < T - 1) { r4 = nr4; d4 = nd4; k4 = nk4; kk4 = nkk4; b4 = nb4; v2 = nv2; }
	v_pk_mul_f32 v[60:61], v[28:29], v[2:3] op_sel:[0,0] op_sel_hi:[0,1]
	v_pk_mul_f32 v[64:65], v[24:25], v[36:37] op_sel:[0,0] op_sel_hi:[0,1]
	v_pk_fma_f32 v[60:61], v[28:29], v[4:5], v[60:61] op_sel:[1,0,0] op_sel_hi:[1,1,1]
	v_pk_mul_f32 v[14:15], v[24:25], v[36:37] op_sel:[1,0] op_sel_hi:[1,1]
	v_pk_fma_f32 v[60:61], v[30:31], v[6:7], v[60:61] op_sel:[0,0,0] op_sel_hi:[0,1,1]
	v_pk_fma_f32 v[2:3], v[20:21], v[2:3], v[64:65] op_sel:[0,0,0] op_sel_hi:[0,1,1]
	v_pk_fma_f32 v[60:61], v[30:31], v[8:9], v[60:61] op_sel:[1,0,0] op_sel_hi:[1,1,1]
	v_pk_fma_f32 v[4:5], v[20:21], v[4:5], v[14:15] op_sel:[1,0,0] op_sel_hi:[1,1,1]
	v_pk_mul_f32 v[64:65], v[26:27], v[36:37] op_sel:[0,0] op_sel_hi:[0,1]
	v_add_f32_dpp v60, v61, v60 quad_perm:[1,0,3,2] row_mask:0xf bank_mask:0xf bound_ctrl:1
	v_pk_mul_f32 v[14:15], v[26:27], v[36:37] op_sel:[1,0] op_sel_hi:[1,1]
	v_pk_fma_f32 v[6:7], v[22:23], v[6:7], v[64:65] op_sel:[0,0,0] op_sel_hi:[0,1,1]
	v_add_f32_dpp v60, v60, v60 quad_perm:[2,3,0,1] row_mask:0xf bank_mask:0xf bound_ctrl:1
	v_add_f32_dpp v62, v63, v62 quad_perm:[1,0,3,2] row_mask:0xf bank_mask:0xf bound_ctrl:1
	v_pk_fma_f32 v[8:9], v[22:23], v[8:9], v[14:15] op_sel:[1,0,0] op_sel_hi:[1,1,1]
	v_add_f32_dpp v60, v60, v60 row_half_mirror row_mask:0xf bank_mask:0xf bound_ctrl:1
	v_add_f32_dpp v62, v62, v62 quad_perm:[2,3,0,1] row_mask:0xf bank_mask:0xf bound_ctrl:1
	ds_read_b128 v[54:57], v250 offset:45568
	v_add_f32_dpp v60, v60, v60 row_mirror row_mask:0xf bank_mask:0xf bound_ctrl:1
	v_add_f32_dpp v62, v62, v62 row_half_mirror row_mask:0xf bank_mask:0xf bound_ctrl:1
	ds_read_b128 v[38:41], v250 offset:44544
	v_mov_b32_dpp v61, v60 quad_perm:[1,0,3,2] row_mask:0xf bank_mask:0xf bound_ctrl:1
	v_add_f32_dpp v62, v62, v62 row_mirror row_mask:0xf bank_mask:0xf bound_ctrl:1
	v_pk_fma_f32 v[2:3], v[32:33], v[60:61], v[2:3] op_sel:[0,0,0] op_sel_hi:[0,1,1] neg_lo:[0,1,0] neg_hi:[0,1,0]
	v_pk_fma_f32 v[4:5], v[32:33], v[60:61], v[4:5] op_sel:[1,0,0] op_sel_hi:[1,1,1] neg_lo:[0,1,0] neg_hi:[0,1,0]
	v_mov_b32_dpp v63, v62 quad_perm:[1,0,3,2] row_mask:0xf bank_mask:0xf bound_ctrl:1
	v_pk_fma_f32 v[6:7], v[34:35], v[60:61], v[6:7] op_sel:[0,0,0] op_sel_hi:[0,1,1] neg_lo:[0,1,0] neg_hi:[0,1,0]
	v_cvt_pk_bf16_f32 v64, v62, v63
	v_pk_fma_f32 v[8:9], v[34:35], v[60:61], v[8:9] op_sel:[1,0,0] op_sel_hi:[1,1,1] neg_lo:[0,1,0] neg_hi:[0,1,0]
	ds_write_b32 v253, v64 offset:3456
	v_pk_mul_f32 v[62:63], v[16:17], v[2:3] op_sel:[0,0] op_sel_hi:[0,1]
	ds_read_b128 v[28:31], v250 offset:46848
	v_pk_fma_f32 v[62:63], v[16:17], v[4:5], v[62:63] op_sel:[1,0,0] op_sel_hi:[1,1,1]
	ds_read_b32 v36, v251 offset:47360
	v_pk_fma_f32 v[62:63], v[18:19], v[6:7], v[62:63] op_sel:[0,0,0] op_sel_hi:[0,1,1]
	ds_read_b32 v37, v252 offset:47360
	v_pk_fma_f32 v[62:63], v[18:19], v[8:9], v[62:63] op_sel:[1,0,0] op_sel_hi:[1,1,1]
	ds_read_b128 v[24:27], v250 offset:46592
	ds_read_b128 v[20:23], v250 offset:46336
	s_waitcnt lgkmcnt(5)
	v_pk_mul_f32 v[60:61], v[50:51], v[2:3] op_sel:[0,0] op_sel_hi:[0,1]
	v_pk_mul_f32 v[64:65], v[46:47], v[58:59] op_sel:[0,0] op_sel_hi:[0,1]
	v_pk_fma_f32 v[60:61], v[50:51], v[4:5], v[60:61] op_sel:[1,0,0] op_sel_hi:[1,1,1]
	v_pk_mul_f32 v[14:15], v[46:47], v[58:59] op_sel:[1,0] op_sel_hi:[1,1]
	v_pk_fma_f32 v[60:61], v[52:53], v[6:7], v[60:61] op_sel:[0,0,0] op_sel_hi:[0,1,1]
	v_pk_fma_f32 v[2:3], v[42:43], v[2:3], v[64:65] op_sel:[0,0,0] op_sel_hi:[0,1,1]
	v_pk_fma_f32 v[60:61], v[52:53], v[8:9], v[60:61] op_sel:[1,0,0] op_sel_hi:[1,1,1]
	v_pk_fma_f32 v[4:5], v[42:43], v[4:5], v[14:15] op_sel:[1,0,0] op_sel_hi:[1,1,1]
	v_pk_mul_f32 v[64:65], v[48:49], v[58:59] op_sel:[0,0] op_sel_hi:[0,1]
	v_add_f32_dpp v60, v61, v60 quad_perm:[1,0,3,2] row_mask:0xf bank_mask:0xf bound_ctrl:1
	v_pk_mul_f32 v[14:15], v[48:49], v[58:59] op_sel:[1,0] op_sel_hi:[1,1]
	v_pk_fma_f32 v[6:7], v[44:45], v[6:7], v[64:65] op_sel:[0,0,0] op_sel_hi:[0,1,1]
	v_add_f32_dpp v60, v60, v60 quad_perm:[2,3,0,1] row_mask:0xf bank_mask:0xf bound_ctrl:1
	v_add_f32_dpp v62, v63, v62 quad_perm:[1,0,3,2] row_mask:0xf bank_mask:0xf bound_ctrl:1
	v_pk_fma_f32 v[8:9], v[44:45], v[8:9], v[14:15] op_sel:[1,0,0] op_sel_hi:[1,1,1]
	v_add_f32_dpp v60, v60, v60 row_half_mirror row_mask:0xf bank_mask:0xf bound_ctrl:1
	v_add_f32_dpp v62, v62, v62 quad_perm:[2,3,0,1] row_mask:0xf bank_mask:0xf bound_ctrl:1
	ds_read_b128 v[32:35], v250 offset:47104
	v_add_f32_dpp v60, v60, v60 row_mirror row_mask:0xf bank_mask:0xf bound_ctrl:1
	v_add_f32_dpp v62, v62, v62 row_half_mirror row_mask:0xf bank_mask:0xf bound_ctrl:1
	ds_read_b128 v[16:19], v250 offset:46080
	v_mov_b32_dpp v61, v60 quad_perm:[1,0,3,2] row_mask:0xf bank_mask:0xf bound_ctrl:1
	v_add_f32_dpp v62, v62, v62 row_mirror row_mask:0xf bank_mask:0xf bound_ctrl:1
	v_pk_fma_f32 v[2:3], v[54:55], v[60:61], v[2:3] op_sel:[0,0,0] op_sel_hi:[0,1,1] neg_lo:[0,1,0] neg_hi:[0,1,0]
	v_pk_fma_f32 v[4:5], v[54:55], v[60:61], v[4:5] op_sel:[1,0,0] op_sel_hi:[1,1,1] neg_lo:[0,1,0] neg_hi:[0,1,0]
	v_mov_b32_dpp v63, v62 quad_perm:[1,0,3,2] row_mask:0xf bank_mask:0xf bound_ctrl:1
	v_pk_fma_f32 v[6:7], v[56:57], v[60:61], v[6:7] op_sel:[0,0,0] op_sel_hi:[0,1,1] neg_lo:[0,1,0] neg_hi:[0,1,0]
	v_cvt_pk_bf16_f32 v64, v62, v63
	v_pk_fma_f32 v[8:9], v[56:57], v[60:61], v[8:9] op_sel:[1,0,0] op_sel_hi:[1,1,1] neg_lo:[0,1,0] neg_hi:[0,1,0]
	ds_write_b32 v253, v64 offset:3584
	v_pk_mul_f32 v[62:63], v[38:39], v[2:3] op_sel:[0,0] op_sel_hi:[0,1]
	ds_read_b128 v[50:53], v250 offset:48384
	v_pk_fma_f32 v[62:63], v[38:39], v[4:5], v[62:63] op_sel:[1,0,0] op_sel_hi:[1,1,1]
	ds_read_b32 v58, v251 offset:48896
	v_pk_fma_f32 v[62:63], v[40:41], v[6:7], v[62:63] op_sel:[0,0,0] op_sel_hi:[0,1,1]
	ds_read_b32 v59, v252 offset:48896
	v_pk_fma_f32 v[62:63], v[40:41], v[8:9], v[62:63] op_sel:[1,0,0] op_sel_hi:[1,1,1]
	ds_read_b128 v[46:49], v250 offset:48128
	ds_read_b128 v[42:45], v250 offset:47872
	s_waitcnt lgkmcnt(5)
; #define LAS __attribute__((address_space(3)))
; DI unsigned pk2(float a, float b) { f32x2 v = {a, b}; bf2_t r = __builtin_convertvector(v, bf2_t); return __builtin_bit_cast(unsigned, r); }
; DI f32x2 red16p(f32x2 x) { float a = x.x, b = x.y; red16x2(a, b); return (f32x2){a, b}; }
; DI void scan_bh2(const Args& a, int l, int bh, int halfsel, LAS unsigned char* lds) {
;     ...
;             for (int st = 0; st < T; ++st) {
;                 f32x4 nr4, nd4, nk4, nkk4, nb4; f32x2 nv2;
;                 if (st < T - 1) {
;                     const LAS float* o = cur + (st + 1) * 384;
;                     nr4 = *(const LAS f32x4*)(o + kq * 4); nd4 = *(const LAS f32x4*)(o + 64 + kq * 4); nk4 = *(const LAS f32x4*)(o + 128 + kq * 4);
;                     nkk4 = *(const LAS f32x4*)(o + 192 + kq * 4); nb4 = *(const LAS f32x4*)(o + 256 + kq * 4); nv2 = *(const LAS f32x2*)(o + 320 + row0);
;                 }
;                 f32x2 sa = S[0] * kk4[0]; sa += S[1] * kk4[1]; f32x2 sb = S[2] * kk4[2]; sb += S[3] * kk4[3]; sa += sb;
;                 sa = red16p(sa); sa = -sa;
; #pragma unroll
;                 for (int j = 0; j < 4; ++j) S[j] = S[j] * d4[j] + sa * b4[j] + v2 * k4[j];
;                 f32x2 y = S[0] * r4[0]; y += S[1] * r4[1]; f32x2 yc = S[2] * r4[2]; yc += S[3] * r4[3]; y += yc;
;                 y = red16p(y);
;                 *(LAS unsigned*)(yb + st * 128 + row0 * 2) = pk2(y.x, y.y);
;                 if (st < T - 1) { r4 = nr4; d4 = nd4; k4 = nk4; kk4 = nkk4; b4 = nb4; v2 = nv2; }
;             }
;             __syncthreads();
;             if (tid < T * 4) { const int rowi = tid >> 2, seg = tid & 3;
;                 *(u32x4*)(Y + ((size_t)b * SEQ + c * T + rowi) * 512 + h * 64 + halfsel * 32 + seg * 8) = *(const LAS u32x4*)(yb + rowi * 128 + halfsel * 64 + seg * 16); }
	v_pk_mul_f32 v[60:61], v[28:29], v[2:3] op_sel:[0,0] op_sel_hi:[0,1]
	v_pk_mul_f32 v[64:65], v[24:25], v[36:37] op_sel:[0,0] op_sel_hi:[0,1]
	v_pk_fma_f32 v[60:61], v[28:29], v[4:5], v[60:61] op_sel:[1,0,0] op_sel_hi:[1,1,1]
	v_pk_mul_f32 v[14:15], v[24:25], v[36:37] op_sel:[1,0] op_sel_hi:[1,1]
	v_pk_fma_f32 v[60:61], v[30:31], v[6:7], v[60:61] op_sel:[0,0,0] op_sel_hi:[0,1,1]
	v_pk_fma_f32 v[2:3], v[20:21], v[2:3], v[64:65] op_sel:[0,0,0] op_sel_hi:[0,1,1]
	v_pk_fma_f32 v[60:61], v[30:31], v[8:9], v[60:61] op_sel:[1,0,0] op_sel_hi:[1,1,1]
	v_pk_fma_f32 v[4:5], v[20:21], v[4:5], v[14:15] op_sel:[1,0,0] op_sel_hi:[1,1,1]
	v_pk_mul_f32 v[64:65], v[26:27], v[36:37] op_sel:[0,0] op_sel_hi:[0,1]
	v_add_f32_dpp v60, v61, v60 quad_perm:[1,0,3,2] row_mask:0xf bank_mask:0xf bound_ctrl:1
	v_pk_mul_f32 v[14:15], v[26:27], v[36:37] op_sel:[1,0] op_sel_hi:[1,1]
	v_pk_fma_f32 v[6:7], v[22:23], v[6:7], v[64:65] op_sel:[0,0,0] op_sel_hi:[0,1,1]
	v_add_f32_dpp v60, v60, v60 quad_perm:[2,3,0,1] row_mask:0xf bank_mask:0xf bound_ctrl:1
	v_add_f32_dpp v62, v63, v62 quad_perm:[1,0,3,2] row_mask:0xf bank_mask:0xf bound_ctrl:1
	v_pk_fma_f32 v[8:9], v[22:23], v[8:9], v[14:15] op_sel:[1,0,0] op_sel_hi:[1,1,1]
	v_add_f32_dpp v60, v60, v60 row_half_mirror row_mask:0xf bank_mask:0xf bound_ctrl:1
	v_add_f32_dpp v62, v62, v62 quad_perm:[2,3,0,1] row_mask:0xf bank_mask:0xf bound_ctrl:1
	ds_read_b128 v[54:57], v250 offset:48640
	v_add_f32_dpp v60, v60, v60 row_mirror row_mask:0xf bank_mask:0xf bound_ctrl:1
	v_add_f32_dpp v62, v62, v62 row_half_mirror row_mask:0xf bank_mask:0xf bound_ctrl:1
	ds_read_b128 v[38:41], v250 offset:47616
	v_mov_b32_dpp v61, v60 quad_perm:[1,0,3,2] row_mask:0xf bank_mask:0xf bound_ctrl:1
	v_add_f32_dpp v62, v62, v62 row_mirror row_mask:0xf bank_mask:0xf bound_ctrl:1
	v_pk_fma_f32 v[2:3], v[32:33], v[60:61], v[2:3] op_sel:[0,0,0] op_sel_hi:[0,1,1] neg_lo:[0,1,0] neg_hi:[0,1,0]
	v_pk_fma_f32 v[4:5], v[32:33], v[60:61], v[4:5] op_sel:[1,0,0] op_sel_hi:[1,1,1] neg_lo:[0,1,0] neg_hi:[0,1,0]
	v_mov_b32_dpp v63, v62 quad_perm:[1,0,3,2] row_mask:0xf bank_mask:0xf bound_ctrl:1
	v_pk_fma_f32 v[6:7], v[34:35], v[60:61], v[6:7] op_sel:[0,0,0] op_sel_hi:[0,1,1] neg_lo:[0,1,0] neg_hi:[0,1,0]
	v_cvt_pk_bf16_f32 v64, v62, v63
	v_pk_fma_f32 v[8:9], v[34:35], v[60:61], v[8:9] op_sel:[1,0,0] op_sel_hi:[1,1,1] neg_lo:[0,1,0] neg_hi:[0,1,0]
	ds_write_b32 v253, v64 offset:3712
	v_pk_mul_f32 v[62:63], v[16:17], v[2:3] op_sel:[0,0] op_sel_hi:[0,1]
	s_nop 0
	v_pk_fma_f32 v[62:63], v[16:17], v[4:5], v[62:63] op_sel:[1,0,0] op_sel_hi:[1,1,1]
	s_nop 0
	v_pk_fma_f32 v[62:63], v[18:19], v[6:7], v[62:63] op_sel:[0,0,0] op_sel_hi:[0,1,1]
	s_nop 0
	v_pk_fma_f32 v[62:63], v[18:19], v[8:9], v[62:63] op_sel:[1,0,0] op_sel_hi:[1,1,1]
	s_waitcnt lgkmcnt(0)
	v_pk_mul_f32 v[60:61], v[50:51], v[2:3] op_sel:[0,0] op_sel_hi:[0,1]
	v_pk_mul_f32 v[64:65], v[46:47], v[58:59] op_sel:[0,0] op_sel_hi:[0,1]
	v_pk_fma_f32 v[60:61], v[50:51], v[4:5], v[60:61] op_sel:[1,0,0] op_sel_hi:[1,1,1]
	v_pk_mul_f32 v[14:15], v[46:47], v[58:59] op_sel:[1,0] op_sel_hi:[1,1]
	v_pk_fma_f32 v[60:61], v[52:53], v[6:7], v[60:61] op_sel:[0,0,0] op_sel_hi:[0,1,1]
	v_pk_fma_f32 v[2:3], v[42:43], v[2:3], v[64:65] op_sel:[0,0,0] op_sel_hi:[0,1,1]
	v_pk_fma_f32 v[60:61], v[52:53], v[8:9], v[60:61] op_sel:[1,0,0] op_sel_hi:[1,1,1]
	v_pk_fma_f32 v[4:5], v[42:43], v[4:5], v[14:15] op_sel:[1,0,0] op_sel_hi:[1,1,1]
	v_pk_mul_f32 v[64:65], v[48:49], v[58:59] op_sel:[0,0] op_sel_hi:[0,1]
	v_add_f32_dpp v60, v61, v60 quad_perm:[1,0,3,2] row_mask:0xf bank_mask:0xf bound_ctrl:1
	v_pk_mul_f32 v[14:15], v[48:49], v[58:59] op_sel:[1,0] op_sel_hi:[1,1]
	v_pk_fma_f32 v[6:7], v[44:45], v[6:7], v[64:65] op_sel:[0,0,0] op_sel_hi:[0,1,1]
	v_add_f32_dpp v60, v60, v60 quad_perm:[2,3,0,1] row_mask:0xf bank_mask:0xf bound_ctrl:1
	v_add_f32_dpp v62, v63, v62 quad_perm:[1,0,3,2] row_mask:0xf bank_mask:0xf bound_ctrl:1
	v_pk_fma_f32 v[8:9], v[44:45], v[8:9], v[14:15] op_sel:[1,0,0] op_sel_hi:[1,1,1]
	v_add_f32_dpp v60, v60, v60 row_half_mirror row_mask:0xf bank_mask:0xf bound_ctrl:1
	v_add_f32_dpp v62, v62, v62 quad_perm:[2,3,0,1] row_mask:0xf bank_mask:0xf bound_ctrl:1
	s_nop 0
	v_add_f32_dpp v60, v60, v60 row_mirror row_mask:0xf bank_mask:0xf bound_ctrl:1
	v_add_f32_dpp v62, v62, v62 row_half_mirror row_mask:0xf bank_mask:0xf bound_ctrl:1
	s_nop 0
	v_mov_b32_dpp v61, v60 quad_perm:[1,0,3,2] row_mask:0xf bank_mask:0xf bound_ctrl:1
	v_add_f32_dpp v62, v62, v62 row_mirror row_mask:0xf bank_mask:0xf bound_ctrl:1
	v_pk_fma_f32 v[2:3], v[54:55], v[60:61], v[2:3] op_sel:[0,0,0] op_sel_hi:[0,1,1] neg_lo:[0,1,0] neg_hi:[0,1,0]
	v_pk_fma_f32 v[4:5], v[54:55], v[60:61], v[4:5] op_sel:[1,0,0] op_sel_hi:[1,1,1] neg_lo:[0,1,0] neg_hi:[0,1,0]
	v_mov_b32_dpp v63, v62 quad_perm:[1,0,3,2] row_mask:0xf bank_mask:0xf bound_ctrl:1
	v_pk_fma_f32 v[6:7], v[56:57], v[60:61], v[6:7] op_sel:[0,0,0] op_sel_hi:[0,1,1] neg_lo:[0,1,0] neg_hi:[0,1,0]
	v_cvt_pk_bf16_f32 v64, v62, v63
	v_pk_fma_f32 v[8:9], v[56:57], v[60:61], v[8:9] op_sel:[1,0,0] op_sel_hi:[1,1,1] neg_lo:[0,1,0] neg_hi:[0,1,0]
	ds_write_b32 v253, v64 offset:3840
	v_pk_mul_f32 v[62:63], v[38:39], v[2:3] op_sel:[0,0] op_sel_hi:[0,1]
	s_nop 0
	v_pk_fma_f32 v[62:63], v[38:39], v[4:5], v[62:63] op_sel:[1,0,0] op_sel_hi:[1,1,1]
	s_nop 0
	v_pk_fma_f32 v[62:63], v[40:41], v[6:7], v[62:63] op_sel:[0,0,0] op_sel_hi:[0,1,1]
	s_nop 0
	v_pk_fma_f32 v[62:63], v[40:41], v[8:9], v[62:63] op_sel:[1,0,0] op_sel_hi:[1,1,1]
	s_nop 1
	v_add_f32_dpp v62, v63, v62 quad_perm:[1,0,3,2] row_mask:0xf bank_mask:0xf bound_ctrl:1
	s_nop 1
	v_add_f32_dpp v62, v62, v62 quad_perm:[2,3,0,1] row_mask:0xf bank_mask:0xf bound_ctrl:1
	s_nop 1
	v_add_f32_dpp v62, v62, v62 row_half_mirror row_mask:0xf bank_mask:0xf bound_ctrl:1
	s_nop 1
	v_add_f32_dpp v62, v62, v62 row_mirror row_mask:0xf bank_mask:0xf bound_ctrl:1
	s_nop 1
	v_mov_b32_dpp v63, v62 quad_perm:[1,0,3,2] row_mask:0xf bank_mask:0xf bound_ctrl:1
	v_cvt_pk_bf16_f32 v64, v62, v63
	ds_write_b32 v253, v64 offset:3968
	s_waitcnt lgkmcnt(0)
	s_barrier
	s_and_saveexec_b64 s[2:3], vcc
	s_cbranch_execz .LBB0_496
	v_readlane_b32 s6, v247, 9
	s_add_i32 s5, s6, s5
	v_add3_u32 v14, s5, v13, v128
	ds_read_b128 v[14:17], v14
	s_waitcnt lgkmcnt(0)
	global_store_dwordx4 v[0:1], v[14:17], off
	s_branch .LBB0_496
